# chunk scan aggregates computed inside the P2b gate-GEMM epilogue from the workgroup's own just-written tile (L2 hits); the separate P2c phase and one grid barrier removed
# speedup vs baseline: 1.0026x; 1.0026x over previous
; __device__ __forceinline__ float bf_lo(unsigned w) { return __uint_as_float(w << 16); }
; __device__ __forceinline__ float bf_hi(unsigned w) { return __uint_as_float(w & 0xffff0000u); }
;     __device__ __forceinline__ void operator()(EPI_ARGS) const {
;         const int c0 = (u.pn >> 1) * 256 + (u.pn & 1) * 128 + wc * 32 + 8 * fq;
;         u32x4 vv[2][4];
; #pragma unroll
;         for (int ai = 0; ai < 2; ++ai)
; #pragma unroll
;             for (int m = 0; m < 4; ++m) vv[ai][m] = *(const u32x4*)(V + (size_t)ROW_OF(ai, m) * LW + c0);
;         f32x4 ba[2], bi[2], sp[2];
; #pragma unroll
;         for (int n = 0; n < 2; ++n) { ba[n] = *(const f32x4*)(b_a + c0 + 4 * n); bi[n] = *(const f32x4*)(b_i + c0 + 4 * n); sp[n] = *(const f32x4*)(sp8 + c0 + 4 * n); }
; #pragma unroll
;         for (int ai = 0; ai < 2; ++ai)
; #pragma unroll
;             for (int m = 0; m < 4; ++m) {
;                 const int row = ROW_OF(ai, m);
; #pragma unroll
;                 for (int n = 0; n < 2; ++n) {
;                     const unsigned w0 = n ? vv[ai][m].z : vv[ai][m].x, w1 = n ? vv[ai][m].w : vv[ai][m].y;
;                     const f32x4 vx = (f32x4){bf_lo(w0), bf_hi(w0), bf_lo(w1), bf_hi(w1)};
;                     const f32x4 r = sigmoid4(acc[ai][0][m][n] + ba[n]), ig = sigmoid4(acc[ai][1][m][n] + bi[n]);
;                     const f32x4 la = sp[n] * r * (-1.4426950409f);
;                     f32x4 av;
; #pragma unroll
;                     for (int j = 0; j < 4; ++j) av[j] = __builtin_amdgcn_exp2f(la[j]);
;                     const f32x4 om = 1.0f - av * av; f32x4 sq;
; #pragma unroll
;                     for (int j = 0; j < 4; ++j) sq[j] = __builtin_amdgcn_sqrtf(om[j]);
;                     const f32x4 bx = sq * ig * vx;
.LBB0_556:
	v_mov_b32_e32 v65, v215
	v_mov_b32_e32 v64, v216
	s_lshl_b32 s0, s27, 7
	s_or_b32 s0, s0, s21
	v_lshl_add_u32 v64, v64, 3, s0
	s_lshl_b32 s0, s74, 8
	s_add_i32 s0, s0, s19
	v_add_u32_e32 v68, s0, v65
	v_ashrrev_i32_e32 v65, 31, v64
	v_ashrrev_i32_e32 v69, 31, v68
	v_lshl_add_u64 v[70:71], v[64:65], 1, s[54:55]
	v_lshlrev_b64 v[66:67], 12, v[68:69]
	v_lshlrev_b64 v[196:197], 2, v[64:65]
	v_lshl_add_u64 v[66:67], v[70:71], 0, v[66:67]
	v_lshl_add_u64 v[64:65], s[38:39], 0, v[196:197]
	global_load_dwordx4 v[180:183], v[66:67], off
	global_load_dwordx4 v[100:103], v[64:65], off
	v_lshl_add_u64 v[66:67], s[42:43], 0, v[196:197]
	global_load_dwordx4 v[92:95], v[66:67], off
	v_lshl_add_u64 v[108:109], s[56:57], 0, v[196:197]
	global_load_dwordx4 v[88:91], v[108:109], off
	global_load_dwordx4 v[80:83], v[64:65], off offset:16
	global_load_dwordx4 v[72:75], v[66:67], off offset:16
	s_nop 0
	global_load_dwordx4 v[64:67], v[108:109], off offset:16
	v_add_u32_e32 v210, 16, v68
	v_add_u32_e32 v208, 32, v68
	v_add_u32_e32 v206, 48, v68
	v_add_u32_e32 v204, 0x80, v68
	v_add_u32_e32 v202, 0x90, v68
	v_add_u32_e32 v200, 0xa0, v68
	v_add_u32_e32 v198, 0xb0, v68
	v_ashrrev_i32_e32 v211, 31, v210
	v_ashrrev_i32_e32 v209, 31, v208
	v_ashrrev_i32_e32 v207, 31, v206
	v_ashrrev_i32_e32 v205, 31, v204
	v_ashrrev_i32_e32 v203, 31, v202
	v_ashrrev_i32_e32 v201, 31, v200
	v_ashrrev_i32_e32 v199, 31, v198
	v_lshlrev_b64 v[222:223], 13, v[68:69]
	v_lshlrev_b64 v[68:69], 12, v[210:211]
	v_lshlrev_b64 v[108:109], 12, v[208:209]
	v_lshlrev_b64 v[110:111], 12, v[206:207]
	v_lshlrev_b64 v[128:129], 12, v[204:205]
	v_lshlrev_b64 v[130:131], 12, v[202:203]
	v_lshlrev_b64 v[148:149], 12, v[200:201]
	v_lshlrev_b64 v[150:151], 12, v[198:199]
	v_lshl_add_u64 v[68:69], v[70:71], 0, v[68:69]
	v_lshl_add_u64 v[108:109], v[70:71], 0, v[108:109]
	v_lshl_add_u64 v[110:111], v[70:71], 0, v[110:111]
	v_lshl_add_u64 v[128:129], v[70:71], 0, v[128:129]
	v_lshl_add_u64 v[130:131], v[70:71], 0, v[130:131]
	v_lshl_add_u64 v[224:225], v[70:71], 0, v[148:149]
	v_lshl_add_u64 v[70:71], v[70:71], 0, v[150:151]
	global_load_dwordx4 v[176:179], v[68:69], off
	global_load_dwordx4 v[172:175], v[108:109], off
	global_load_dwordx4 v[164:167], v[110:111], off
	global_load_dwordx4 v[148:151], v[128:129], off
	s_nop 0
	global_load_dwordx4 v[128:131], v[130:131], off
	s_nop 0
	global_load_dwordx4 v[108:111], v[224:225], off
	s_nop 0
	global_load_dwordx4 v[68:71], v[70:71], off
	v_readlane_b32 s80, v248, 11
	v_readlane_b32 s92, v248, 23
	v_readlane_b32 s93, v248, 24
	v_readlane_b32 s81, v248, 12
	v_readlane_b32 s82, v248, 13
	v_readlane_b32 s83, v248, 14
	v_readlane_b32 s84, v248, 15
	v_readlane_b32 s85, v248, 16
	v_readlane_b32 s86, v248, 17
	v_readlane_b32 s87, v248, 18
	v_readlane_b32 s88, v248, 19
	v_readlane_b32 s89, v248, 20
	v_readlane_b32 s90, v248, 21
	v_readlane_b32 s91, v248, 22
	v_readlane_b32 s94, v248, 25
	v_readlane_b32 s95, v248, 26
	s_and_b64 vcc, exec, s[4:5]
	s_mov_b64 s[0:1], -1
	s_waitcnt vmcnt(0)
	v_lshlrev_b32_e32 v224, 16, v180
	v_pk_add_f32 v[168:169], v[168:169], v[100:101]
	v_pk_add_f32 v[170:171], v[170:171], v[102:103]
	v_pk_add_f32 v[160:161], v[160:161], v[92:93]
	v_mul_f32_e32 v168, 0xbfb8aa3b, v168
	v_mul_f32_e32 v169, 0xbfb8aa3b, v169
	v_mul_f32_e32 v170, 0xbfb8aa3b, v170
	v_mul_f32_e32 v171, 0xbfb8aa3b, v171
	v_mul_f32_e32 v160, 0xbfb8aa3b, v160
	v_mul_f32_e32 v161, 0xbfb8aa3b, v161
	v_exp_f32_e32 v168, v168
	v_exp_f32_e32 v169, v169
	v_pk_add_f32 v[162:163], v[162:163], v[94:95]
	v_exp_f32_e32 v170, v170
	v_exp_f32_e32 v171, v171
	v_exp_f32_e32 v160, v160
	v_exp_f32_e32 v161, v161
	v_mul_f32_e32 v162, 0xbfb8aa3b, v162
	v_mul_f32_e32 v163, 0xbfb8aa3b, v163
	v_exp_f32_e32 v162, v162
	v_and_b32_e32 v225, 0xffff0000, v180
	v_exp_f32_e32 v180, v163
	v_add_f32_e32 v163, 1.0, v168
	v_add_f32_e32 v168, 1.0, v169
	v_add_f32_e32 v169, 1.0, v170
	v_add_f32_e32 v170, 1.0, v171
	v_add_f32_e32 v171, 1.0, v160
	v_add_f32_e32 v221, 1.0, v161
	v_rcp_f32_e32 v160, v163
	v_rcp_f32_e32 v161, v168
	v_add_f32_e32 v226, 1.0, v162
	v_rcp_f32_e32 v162, v169
	v_rcp_f32_e32 v163, v170
	v_pk_mul_f32 v[160:161], v[88:89], v[160:161]
	v_rcp_f32_e32 v170, v226
	v_pk_mul_f32 v[160:161], v[160:161], s[62:63] op_sel_hi:[1,0]
	v_pk_mul_f32 v[162:163], v[90:91], v[162:163]
	v_exp_f32_e32 v226, v160
	v_exp_f32_e32 v227, v161
	v_pk_mul_f32 v[162:163], v[162:163], s[62:63] op_sel_hi:[1,0]
	v_pk_add_f32 v[156:157], v[156:157], v[80:81]
	v_exp_f32_e32 v228, v162
	v_exp_f32_e32 v229, v163
	v_pk_add_f32 v[158:159], v[158:159], v[82:83]
	v_mul_f32_e32 v156, 0xbfb8aa3b, v156
	v_mul_f32_e32 v157, 0xbfb8aa3b, v157
	v_pk_mul_f32 v[226:227], v[226:227], v[226:227]
	v_exp_f32_e32 v156, v156
	v_exp_f32_e32 v157, v157
	v_mul_f32_e32 v158, 0xbfb8aa3b, v158
	v_mul_f32_e32 v159, 0xbfb8aa3b, v159
	v_rcp_f32_e32 v168, v171
	v_add_f32_e32 v171, 1.0, v180
	v_sub_f32_e32 v180, 1.0, v226
	v_exp_f32_e32 v158, v158
	v_exp_f32_e32 v159, v159
	v_pk_mul_f32 v[228:229], v[228:229], v[228:229]
	v_sqrt_f32_e32 v226, v180
	v_sub_f32_e32 v180, 1.0, v227
	v_rcp_f32_e32 v169, v221
	v_sub_f32_e32 v221, 1.0, v228
	v_sqrt_f32_e32 v227, v180
	v_sqrt_f32_e32 v228, v221
	v_sub_f32_e32 v221, 1.0, v229
	v_add_f32_e32 v156, 1.0, v156
	v_add_f32_e32 v157, 1.0, v157
	v_rcp_f32_e32 v171, v171
	v_sqrt_f32_e32 v229, v221
	v_rcp_f32_e32 v156, v156
	v_rcp_f32_e32 v157, v157
	v_add_f32_e32 v158, 1.0, v158
	v_add_f32_e32 v159, 1.0, v159
	v_rcp_f32_e32 v158, v158
	v_rcp_f32_e32 v159, v159
	v_pk_mul_f32 v[168:169], v[168:169], v[226:227]
	v_lshlrev_b32_e32 v180, 16, v181
	v_pk_mul_f32 v[168:169], v[168:169], v[224:225]
	v_and_b32_e32 v181, 0xffff0000, v181
; __device__ __forceinline__ unsigned cvt_pk_bf16(float lo, float hi) { unsigned r; asm volatile("v_cvt_pk_bf16_f32 %0, %1, %2" : "=v"(r) : "v"(lo), "v"(hi)); return r; }
; __device__ __forceinline__ float bf_lo(unsigned w) { return __uint_as_float(w << 16); }
; __device__ __forceinline__ float bf_hi(unsigned w) { return __uint_as_float(w & 0xffff0000u); }
;     __device__ __forceinline__ void operator()(EPI_ARGS) const {
;     ...
;         for (int ai = 0; ai < 2; ++ai)
; #pragma unroll
;             for (int m = 0; m < 4; ++m) {
;                 const int row = ROW_OF(ai, m);
; #pragma unroll
;                 for (int n = 0; n < 2; ++n) {
;                     const unsigned w0 = n ? vv[ai][m].z : vv[ai][m].x, w1 = n ? vv[ai][m].w : vv[ai][m].y;
;                     const f32x4 vx = (f32x4){bf_lo(w0), bf_hi(w0), bf_lo(w1), bf_hi(w1)};
;                     const f32x4 r = sigmoid4(acc[ai][0][m][n] + ba[n]), ig = sigmoid4(acc[ai][1][m][n] + bi[n]);
;                     const f32x4 la = sp[n] * r * (-1.4426950409f);
;                     f32x4 av;
; #pragma unroll
;                     for (int j = 0; j < 4; ++j) av[j] = __builtin_amdgcn_exp2f(la[j]);
;                     const f32x4 om = 1.0f - av * av; f32x4 sq;
; #pragma unroll
;                     for (int j = 0; j < 4; ++j) sq[j] = __builtin_amdgcn_sqrtf(om[j]);
;                     const f32x4 bx = sq * ig * vx;
;                     u32x4 w; w.x = cvt_pk_bf16(la[0], bx[0]); w.y = cvt_pk_bf16(la[1], bx[1]); w.z = cvt_pk_bf16(la[2], bx[2]); w.w = cvt_pk_bf16(la[3], bx[3]);
;                     *(u32x4*)(AB + (size_t)row * LW + c0 + 4 * n) = w;
	v_pk_mul_f32 v[170:171], v[170:171], v[228:229]
	v_cvt_pk_bf16_f32 v160, v160, v168
	v_cvt_pk_bf16_f32 v161, v161, v169
	v_lshl_add_u64 v[168:169], s[92:93], 0, v[222:223]
	v_pk_mul_f32 v[156:157], v[64:65], v[156:157]
	v_pk_mul_f32 v[170:171], v[170:171], v[180:181]
	v_lshl_add_u64 v[168:169], v[168:169], 0, v[196:197]
	v_cvt_pk_bf16_f32 v162, v162, v170
	v_cvt_pk_bf16_f32 v163, v163, v171
	v_pk_add_f32 v[152:153], v[152:153], v[72:73]
	v_pk_mul_f32 v[158:159], v[66:67], v[158:159]
	v_pk_mul_f32 v[156:157], v[156:157], s[62:63] op_sel_hi:[1,0]
	v_pk_add_f32 v[144:145], v[144:145], v[100:101]
	global_store_dwordx4 v[168:169], v[160:163], off
	v_pk_add_f32 v[154:155], v[154:155], v[74:75]
	v_mul_f32_e32 v152, 0xbfb8aa3b, v152
	v_mul_f32_e32 v153, 0xbfb8aa3b, v153
	v_pk_mul_f32 v[158:159], v[158:159], s[62:63] op_sel_hi:[1,0]
	v_exp_f32_e32 v162, v156
	v_exp_f32_e32 v163, v157
	v_pk_add_f32 v[146:147], v[146:147], v[102:103]
	v_mul_f32_e32 v144, 0xbfb8aa3b, v144
	v_mul_f32_e32 v145, 0xbfb8aa3b, v145
	v_exp_f32_e32 v152, v152
	v_exp_f32_e32 v153, v153
	v_mul_f32_e32 v154, 0xbfb8aa3b, v154
	v_mul_f32_e32 v155, 0xbfb8aa3b, v155
	v_exp_f32_e32 v170, v158
	v_exp_f32_e32 v171, v159
	v_exp_f32_e32 v144, v144
	v_exp_f32_e32 v145, v145
	v_mul_f32_e32 v146, 0xbfb8aa3b, v146
	v_mul_f32_e32 v147, 0xbfb8aa3b, v147
	v_exp_f32_e32 v154, v154
	v_exp_f32_e32 v155, v155
	v_exp_f32_e32 v146, v146
	v_exp_f32_e32 v147, v147
	v_pk_mul_f32 v[162:163], v[162:163], v[162:163]
	v_add_f32_e32 v152, 1.0, v152
	v_add_f32_e32 v153, 1.0, v153
	v_pk_mul_f32 v[170:171], v[170:171], v[170:171]
	v_sub_f32_e32 v162, 1.0, v162
	v_sub_f32_e32 v163, 1.0, v163
	v_add_f32_e32 v144, 1.0, v144
	v_add_f32_e32 v145, 1.0, v145
	v_rcp_f32_e32 v152, v152
	v_rcp_f32_e32 v153, v153
	v_add_f32_e32 v154, 1.0, v154
	v_add_f32_e32 v155, 1.0, v155
	v_sqrt_f32_e32 v162, v162
	v_sub_f32_e32 v170, 1.0, v170
	v_sub_f32_e32 v171, 1.0, v171
	v_sqrt_f32_e32 v163, v163
	v_rcp_f32_e32 v144, v144
	v_rcp_f32_e32 v145, v145
	v_add_f32_e32 v146, 1.0, v146
	v_add_f32_e32 v147, 1.0, v147
	v_rcp_f32_e32 v154, v154
	v_rcp_f32_e32 v155, v155
	v_sqrt_f32_e32 v170, v170
	v_sqrt_f32_e32 v171, v171
	v_rcp_f32_e32 v146, v146
	v_rcp_f32_e32 v147, v147
	v_lshlrev_b32_e32 v160, 16, v182
	v_and_b32_e32 v161, 0xffff0000, v182
	v_pk_mul_f32 v[152:153], v[152:153], v[162:163]
	v_pk_mul_f32 v[144:145], v[88:89], v[144:145]
	v_lshlrev_b32_e32 v180, 16, v183
	v_and_b32_e32 v181, 0xffff0000, v183
	v_pk_mul_f32 v[154:155], v[154:155], v[170:171]
	v_pk_mul_f32 v[152:153], v[152:153], v[160:161]
	v_pk_add_f32 v[140:141], v[140:141], v[92:93]
	v_pk_mul_f32 v[146:147], v[90:91], v[146:147]
	v_pk_mul_f32 v[144:145], v[144:145], s[62:63] op_sel_hi:[1,0]
	v_pk_mul_f32 v[154:155], v[154:155], v[180:181]
	v_cvt_pk_bf16_f32 v152, v156, v152
	v_cvt_pk_bf16_f32 v153, v157, v153
	v_pk_add_f32 v[142:143], v[142:143], v[94:95]
	v_mul_f32_e32 v140, 0xbfb8aa3b, v140
	v_mul_f32_e32 v141, 0xbfb8aa3b, v141
	v_pk_mul_f32 v[146:147], v[146:147], s[62:63] op_sel_hi:[1,0]
	v_exp_f32_e32 v156, v144
	v_exp_f32_e32 v157, v145
	v_cvt_pk_bf16_f32 v154, v158, v154
	v_cvt_pk_bf16_f32 v155, v159, v155
	v_exp_f32_e32 v140, v140
	v_exp_f32_e32 v141, v141
	v_mul_f32_e32 v142, 0xbfb8aa3b, v142
	v_mul_f32_e32 v143, 0xbfb8aa3b, v143
	v_exp_f32_e32 v158, v146
	v_exp_f32_e32 v159, v147
	v_pk_add_f32 v[136:137], v[136:137], v[80:81]
	v_exp_f32_e32 v142, v142
	v_exp_f32_e32 v143, v143
	v_pk_add_f32 v[138:139], v[138:139], v[82:83]
	v_mul_f32_e32 v136, 0xbfb8aa3b, v136
	v_mul_f32_e32 v137, 0xbfb8aa3b, v137
	v_exp_f32_e32 v136, v136
	v_exp_f32_e32 v137, v137
	v_mul_f32_e32 v138, 0xbfb8aa3b, v138
	v_mul_f32_e32 v139, 0xbfb8aa3b, v139
	v_pk_mul_f32 v[156:157], v[156:157], v[156:157]
	v_exp_f32_e32 v138, v138
	v_exp_f32_e32 v139, v139
	v_add_f32_e32 v140, 1.0, v140
	v_add_f32_e32 v141, 1.0, v141
	v_pk_mul_f32 v[158:159], v[158:159], v[158:159]
	v_sub_f32_e32 v156, 1.0, v156
	v_sub_f32_e32 v157, 1.0, v157
	v_rcp_f32_e32 v140, v140
	v_rcp_f32_e32 v141, v141
	v_add_f32_e32 v142, 1.0, v142
	v_add_f32_e32 v143, 1.0, v143
	v_sqrt_f32_e32 v156, v156
	v_sub_f32_e32 v158, 1.0, v158
	v_sub_f32_e32 v159, 1.0, v159
	v_sqrt_f32_e32 v157, v157
	v_rcp_f32_e32 v142, v142
	v_rcp_f32_e32 v143, v143
	v_sqrt_f32_e32 v158, v158
	v_sqrt_f32_e32 v159, v159
	v_add_f32_e32 v136, 1.0, v136
	v_add_f32_e32 v137, 1.0, v137
	v_rcp_f32_e32 v136, v136
	v_rcp_f32_e32 v137, v137
	v_add_f32_e32 v138, 1.0, v138
	v_add_f32_e32 v139, 1.0, v139
	v_rcp_f32_e32 v138, v138
	v_rcp_f32_e32 v139, v139
	global_store_dwordx4 v[168:169], v[152:155], off offset:16
	v_pk_mul_f32 v[140:141], v[140:141], v[156:157]
	v_lshlrev_b32_e32 v160, 16, v177
	v_lshlrev_b32_e32 v154, 16, v176
	v_and_b32_e32 v155, 0xffff0000, v176
	v_lshlrev_b64 v[152:153], 13, v[210:211]
	v_and_b32_e32 v161, 0xffff0000, v177
	v_pk_mul_f32 v[142:143], v[142:143], v[158:159]
	v_pk_mul_f32 v[140:141], v[140:141], v[154:155]
	v_pk_mul_f32 v[142:143], v[142:143], v[160:161]
	v_cvt_pk_bf16_f32 v140, v144, v140
	v_cvt_pk_bf16_f32 v141, v145, v141
	v_lshl_add_u64 v[144:145], s[92:93], 0, v[152:153]
	v_pk_mul_f32 v[136:137], v[64:65], v[136:137]
	v_cvt_pk_bf16_f32 v142, v146, v142
	v_cvt_pk_bf16_f32 v143, v147, v143
	v_lshl_add_u64 v[144:145], v[144:145], 0, v[196:197]
	v_pk_add_f32 v[132:133], v[132:133], v[72:73]
	v_pk_mul_f32 v[138:139], v[66:67], v[138:139]
	v_pk_mul_f32 v[136:137], v[136:137], s[62:63] op_sel_hi:[1,0]
	v_pk_add_f32 v[124:125], v[124:125], v[100:101]
	global_store_dwordx4 v[144:145], v[140:143], off
	v_pk_add_f32 v[134:135], v[134:135], v[74:75]
	v_mul_f32_e32 v132, 0xbfb8aa3b, v132
	v_mul_f32_e32 v133, 0xbfb8aa3b, v133
; __device__ __forceinline__ unsigned cvt_pk_bf16(float lo, float hi) { unsigned r; asm volatile("v_cvt_pk_bf16_f32 %0, %1, %2" : "=v"(r) : "v"(lo), "v"(hi)); return r; }
; __device__ __forceinline__ float bf_lo(unsigned w) { return __uint_as_float(w << 16); }
; __device__ __forceinline__ float bf_hi(unsigned w) { return __uint_as_float(w & 0xffff0000u); }
;     __device__ __forceinline__ void operator()(EPI_ARGS) const {
;     ...
;         for (int ai = 0; ai < 2; ++ai)
; #pragma unroll
;             for (int m = 0; m < 4; ++m) {
;                 const int row = ROW_OF(ai, m);
; #pragma unroll
;                 for (int n = 0; n < 2; ++n) {
;                     const unsigned w0 = n ? vv[ai][m].z : vv[ai][m].x, w1 = n ? vv[ai][m].w : vv[ai][m].y;
;                     const f32x4 vx = (f32x4){bf_lo(w0), bf_hi(w0), bf_lo(w1), bf_hi(w1)};
;                     const f32x4 r = sigmoid4(acc[ai][0][m][n] + ba[n]), ig = sigmoid4(acc[ai][1][m][n] + bi[n]);
;                     const f32x4 la = sp[n] * r * (-1.4426950409f);
;                     f32x4 av;
; #pragma unroll
;                     for (int j = 0; j < 4; ++j) av[j] = __builtin_amdgcn_exp2f(la[j]);
;                     const f32x4 om = 1.0f - av * av; f32x4 sq;
; #pragma unroll
;                     for (int j = 0; j < 4; ++j) sq[j] = __builtin_amdgcn_sqrtf(om[j]);
;                     const f32x4 bx = sq * ig * vx;
;                     u32x4 w; w.x = cvt_pk_bf16(la[0], bx[0]); w.y = cvt_pk_bf16(la[1], bx[1]); w.z = cvt_pk_bf16(la[2], bx[2]); w.w = cvt_pk_bf16(la[3], bx[3]);
;                     *(u32x4*)(AB + (size_t)row * LW + c0 + 4 * n) = w;
	v_pk_mul_f32 v[138:139], v[138:139], s[62:63] op_sel_hi:[1,0]
	v_exp_f32_e32 v142, v136
	v_exp_f32_e32 v143, v137
	v_pk_add_f32 v[126:127], v[126:127], v[102:103]
	v_mul_f32_e32 v124, 0xbfb8aa3b, v124
	v_mul_f32_e32 v125, 0xbfb8aa3b, v125
	v_exp_f32_e32 v132, v132
	v_exp_f32_e32 v133, v133
	v_mul_f32_e32 v134, 0xbfb8aa3b, v134
	v_mul_f32_e32 v135, 0xbfb8aa3b, v135
	v_exp_f32_e32 v146, v138
	v_exp_f32_e32 v147, v139
	v_exp_f32_e32 v124, v124
	v_exp_f32_e32 v125, v125
	v_mul_f32_e32 v126, 0xbfb8aa3b, v126
	v_mul_f32_e32 v127, 0xbfb8aa3b, v127
	v_exp_f32_e32 v134, v134
	v_exp_f32_e32 v135, v135
	v_exp_f32_e32 v126, v126
	v_exp_f32_e32 v127, v127
	v_pk_mul_f32 v[142:143], v[142:143], v[142:143]
	v_add_f32_e32 v132, 1.0, v132
	v_add_f32_e32 v133, 1.0, v133
	v_pk_mul_f32 v[146:147], v[146:147], v[146:147]
	v_sub_f32_e32 v142, 1.0, v142
	v_sub_f32_e32 v143, 1.0, v143
	v_add_f32_e32 v124, 1.0, v124
	v_add_f32_e32 v125, 1.0, v125
	v_rcp_f32_e32 v132, v132
	v_rcp_f32_e32 v133, v133
	v_add_f32_e32 v134, 1.0, v134
	v_add_f32_e32 v135, 1.0, v135
	v_sqrt_f32_e32 v142, v142
	v_sub_f32_e32 v146, 1.0, v146
	v_sub_f32_e32 v147, 1.0, v147
	v_sqrt_f32_e32 v143, v143
	v_rcp_f32_e32 v124, v124
	v_rcp_f32_e32 v125, v125
	v_add_f32_e32 v126, 1.0, v126
	v_add_f32_e32 v127, 1.0, v127
	v_rcp_f32_e32 v134, v134
	v_rcp_f32_e32 v135, v135
	v_sqrt_f32_e32 v146, v146
	v_sqrt_f32_e32 v147, v147
	v_rcp_f32_e32 v126, v126
	v_rcp_f32_e32 v127, v127
	v_lshlrev_b32_e32 v140, 16, v178
	v_and_b32_e32 v141, 0xffff0000, v178
	v_pk_mul_f32 v[132:133], v[132:133], v[142:143]
	v_pk_mul_f32 v[124:125], v[88:89], v[124:125]
	v_lshlrev_b32_e32 v152, 16, v179
	v_and_b32_e32 v153, 0xffff0000, v179
	v_pk_mul_f32 v[134:135], v[134:135], v[146:147]
	v_pk_mul_f32 v[132:133], v[132:133], v[140:141]
	v_pk_add_f32 v[120:121], v[120:121], v[92:93]
	v_pk_mul_f32 v[126:127], v[90:91], v[126:127]
	v_pk_mul_f32 v[124:125], v[124:125], s[62:63] op_sel_hi:[1,0]
	v_pk_mul_f32 v[134:135], v[134:135], v[152:153]
	v_cvt_pk_bf16_f32 v132, v136, v132
	v_cvt_pk_bf16_f32 v133, v137, v133
	v_pk_add_f32 v[122:123], v[122:123], v[94:95]
	v_mul_f32_e32 v120, 0xbfb8aa3b, v120
	v_mul_f32_e32 v121, 0xbfb8aa3b, v121
	v_pk_mul_f32 v[126:127], v[126:127], s[62:63] op_sel_hi:[1,0]
	v_exp_f32_e32 v136, v124
	v_exp_f32_e32 v137, v125
	v_cvt_pk_bf16_f32 v134, v138, v134
	v_cvt_pk_bf16_f32 v135, v139, v135
	v_exp_f32_e32 v120, v120
	v_exp_f32_e32 v121, v121
	v_mul_f32_e32 v122, 0xbfb8aa3b, v122
	v_mul_f32_e32 v123, 0xbfb8aa3b, v123
	v_exp_f32_e32 v138, v126
	v_exp_f32_e32 v139, v127
	v_pk_add_f32 v[116:117], v[116:117], v[80:81]
	v_exp_f32_e32 v122, v122
	v_exp_f32_e32 v123, v123
	v_pk_add_f32 v[118:119], v[118:119], v[82:83]
	v_mul_f32_e32 v116, 0xbfb8aa3b, v116
	v_mul_f32_e32 v117, 0xbfb8aa3b, v117
	v_exp_f32_e32 v116, v116
	v_exp_f32_e32 v117, v117
	v_mul_f32_e32 v118, 0xbfb8aa3b, v118
	v_mul_f32_e32 v119, 0xbfb8aa3b, v119
	v_pk_mul_f32 v[136:137], v[136:137], v[136:137]
	v_exp_f32_e32 v118, v118
	v_exp_f32_e32 v119, v119
	v_add_f32_e32 v120, 1.0, v120
	v_add_f32_e32 v121, 1.0, v121
	v_pk_mul_f32 v[138:139], v[138:139], v[138:139]
	v_sub_f32_e32 v136, 1.0, v136
	v_sub_f32_e32 v137, 1.0, v137
	v_rcp_f32_e32 v120, v120
	v_rcp_f32_e32 v121, v121
	v_add_f32_e32 v122, 1.0, v122
	v_add_f32_e32 v123, 1.0, v123
	v_sqrt_f32_e32 v136, v136
	v_sub_f32_e32 v138, 1.0, v138
	v_sub_f32_e32 v139, 1.0, v139
	v_sqrt_f32_e32 v137, v137
	v_rcp_f32_e32 v122, v122
	v_rcp_f32_e32 v123, v123
	v_sqrt_f32_e32 v138, v138
	v_sqrt_f32_e32 v139, v139
	v_add_f32_e32 v116, 1.0, v116
	v_add_f32_e32 v117, 1.0, v117
	v_rcp_f32_e32 v116, v116
	v_rcp_f32_e32 v117, v117
	v_add_f32_e32 v118, 1.0, v118
	v_add_f32_e32 v119, 1.0, v119
	v_rcp_f32_e32 v118, v118
	v_rcp_f32_e32 v119, v119
	global_store_dwordx4 v[144:145], v[132:135], off offset:16
	v_pk_mul_f32 v[120:121], v[120:121], v[136:137]
	v_lshlrev_b32_e32 v140, 16, v173
	v_lshlrev_b32_e32 v134, 16, v172
	v_and_b32_e32 v135, 0xffff0000, v172
	v_lshlrev_b64 v[132:133], 13, v[208:209]
	v_and_b32_e32 v141, 0xffff0000, v173
	v_pk_mul_f32 v[122:123], v[122:123], v[138:139]
	v_pk_mul_f32 v[120:121], v[120:121], v[134:135]
	v_pk_mul_f32 v[122:123], v[122:123], v[140:141]
	v_cvt_pk_bf16_f32 v120, v124, v120
	v_cvt_pk_bf16_f32 v121, v125, v121
	v_lshl_add_u64 v[124:125], s[92:93], 0, v[132:133]
	v_pk_mul_f32 v[116:117], v[64:65], v[116:117]
	v_cvt_pk_bf16_f32 v122, v126, v122
	v_cvt_pk_bf16_f32 v123, v127, v123
	v_lshl_add_u64 v[124:125], v[124:125], 0, v[196:197]
	v_pk_add_f32 v[112:113], v[112:113], v[72:73]
	v_pk_mul_f32 v[118:119], v[66:67], v[118:119]
	v_pk_mul_f32 v[116:117], v[116:117], s[62:63] op_sel_hi:[1,0]
	v_pk_add_f32 v[104:105], v[104:105], v[100:101]
	global_store_dwordx4 v[124:125], v[120:123], off
	v_pk_add_f32 v[114:115], v[114:115], v[74:75]
	v_mul_f32_e32 v112, 0xbfb8aa3b, v112
	v_mul_f32_e32 v113, 0xbfb8aa3b, v113
	v_pk_mul_f32 v[118:119], v[118:119], s[62:63] op_sel_hi:[1,0]
	v_exp_f32_e32 v122, v116
	v_exp_f32_e32 v123, v117
	v_pk_add_f32 v[106:107], v[106:107], v[102:103]
	v_mul_f32_e32 v104, 0xbfb8aa3b, v104
	v_mul_f32_e32 v105, 0xbfb8aa3b, v105
	v_exp_f32_e32 v112, v112
	v_exp_f32_e32 v113, v113
	v_mul_f32_e32 v114, 0xbfb8aa3b, v114
	v_mul_f32_e32 v115, 0xbfb8aa3b, v115
	v_exp_f32_e32 v126, v118
	v_exp_f32_e32 v127, v119
	v_exp_f32_e32 v104, v104
	v_exp_f32_e32 v105, v105
	v_mul_f32_e32 v106, 0xbfb8aa3b, v106
	v_mul_f32_e32 v107, 0xbfb8aa3b, v107
	v_exp_f32_e32 v114, v114
	v_exp_f32_e32 v115, v115
	v_exp_f32_e32 v106, v106
	v_exp_f32_e32 v107, v107
	v_pk_mul_f32 v[122:123], v[122:123], v[122:123]
	v_add_f32_e32 v112, 1.0, v112
	v_add_f32_e32 v113, 1.0, v113
	v_pk_mul_f32 v[126:127], v[126:127], v[126:127]
; __device__ __forceinline__ unsigned cvt_pk_bf16(float lo, float hi) { unsigned r; asm volatile("v_cvt_pk_bf16_f32 %0, %1, %2" : "=v"(r) : "v"(lo), "v"(hi)); return r; }
; __device__ __forceinline__ float bf_lo(unsigned w) { return __uint_as_float(w << 16); }
; __device__ __forceinline__ float bf_hi(unsigned w) { return __uint_as_float(w & 0xffff0000u); }
;     __device__ __forceinline__ void operator()(EPI_ARGS) const {
;     ...
;         for (int ai = 0; ai < 2; ++ai)
; #pragma unroll
;             for (int m = 0; m < 4; ++m) {
;                 const int row = ROW_OF(ai, m);
; #pragma unroll
;                 for (int n = 0; n < 2; ++n) {
;                     const unsigned w0 = n ? vv[ai][m].z : vv[ai][m].x, w1 = n ? vv[ai][m].w : vv[ai][m].y;
;                     const f32x4 vx = (f32x4){bf_lo(w0), bf_hi(w0), bf_lo(w1), bf_hi(w1)};
;                     const f32x4 r = sigmoid4(acc[ai][0][m][n] + ba[n]), ig = sigmoid4(acc[ai][1][m][n] + bi[n]);
;                     const f32x4 la = sp[n] * r * (-1.4426950409f);
;                     f32x4 av;
; #pragma unroll
;                     for (int j = 0; j < 4; ++j) av[j] = __builtin_amdgcn_exp2f(la[j]);
;                     const f32x4 om = 1.0f - av * av; f32x4 sq;
; #pragma unroll
;                     for (int j = 0; j < 4; ++j) sq[j] = __builtin_amdgcn_sqrtf(om[j]);
;                     const f32x4 bx = sq * ig * vx;
;                     u32x4 w; w.x = cvt_pk_bf16(la[0], bx[0]); w.y = cvt_pk_bf16(la[1], bx[1]); w.z = cvt_pk_bf16(la[2], bx[2]); w.w = cvt_pk_bf16(la[3], bx[3]);
;                     *(u32x4*)(AB + (size_t)row * LW + c0 + 4 * n) = w;
	v_sub_f32_e32 v122, 1.0, v122
	v_sub_f32_e32 v123, 1.0, v123
	v_add_f32_e32 v104, 1.0, v104
	v_add_f32_e32 v105, 1.0, v105
	v_rcp_f32_e32 v112, v112
	v_rcp_f32_e32 v113, v113
	v_add_f32_e32 v114, 1.0, v114
	v_add_f32_e32 v115, 1.0, v115
	v_sqrt_f32_e32 v122, v122
	v_sub_f32_e32 v126, 1.0, v126
	v_sub_f32_e32 v127, 1.0, v127
	v_sqrt_f32_e32 v123, v123
	v_rcp_f32_e32 v104, v104
	v_rcp_f32_e32 v105, v105
	v_add_f32_e32 v106, 1.0, v106
	v_add_f32_e32 v107, 1.0, v107
	v_rcp_f32_e32 v114, v114
	v_rcp_f32_e32 v115, v115
	v_sqrt_f32_e32 v126, v126
	v_sqrt_f32_e32 v127, v127
	v_rcp_f32_e32 v106, v106
	v_rcp_f32_e32 v107, v107
	v_lshlrev_b32_e32 v120, 16, v174
	v_and_b32_e32 v121, 0xffff0000, v174
	v_pk_mul_f32 v[112:113], v[112:113], v[122:123]
	v_pk_mul_f32 v[104:105], v[88:89], v[104:105]
	v_lshlrev_b32_e32 v132, 16, v175
	v_and_b32_e32 v133, 0xffff0000, v175
	v_pk_mul_f32 v[114:115], v[114:115], v[126:127]
	v_pk_mul_f32 v[112:113], v[112:113], v[120:121]
	v_pk_add_f32 v[96:97], v[96:97], v[92:93]
	v_pk_mul_f32 v[106:107], v[90:91], v[106:107]
	v_pk_mul_f32 v[104:105], v[104:105], s[62:63] op_sel_hi:[1,0]
	v_pk_mul_f32 v[114:115], v[114:115], v[132:133]
	v_cvt_pk_bf16_f32 v112, v116, v112
	v_cvt_pk_bf16_f32 v113, v117, v113
	v_pk_add_f32 v[98:99], v[98:99], v[94:95]
	v_mul_f32_e32 v96, 0xbfb8aa3b, v96
	v_mul_f32_e32 v97, 0xbfb8aa3b, v97
	v_pk_mul_f32 v[106:107], v[106:107], s[62:63] op_sel_hi:[1,0]
	v_exp_f32_e32 v116, v104
	v_exp_f32_e32 v117, v105
	v_cvt_pk_bf16_f32 v114, v118, v114
	v_cvt_pk_bf16_f32 v115, v119, v115
	v_exp_f32_e32 v96, v96
	v_exp_f32_e32 v97, v97
	v_mul_f32_e32 v98, 0xbfb8aa3b, v98
	v_mul_f32_e32 v99, 0xbfb8aa3b, v99
	v_exp_f32_e32 v118, v106
	v_exp_f32_e32 v119, v107
	v_pk_add_f32 v[84:85], v[84:85], v[80:81]
	v_exp_f32_e32 v98, v98
	v_exp_f32_e32 v99, v99
	v_pk_add_f32 v[86:87], v[86:87], v[82:83]
	v_mul_f32_e32 v84, 0xbfb8aa3b, v84
	v_mul_f32_e32 v85, 0xbfb8aa3b, v85
	v_exp_f32_e32 v84, v84
	v_exp_f32_e32 v85, v85
	v_mul_f32_e32 v86, 0xbfb8aa3b, v86
	v_mul_f32_e32 v87, 0xbfb8aa3b, v87
	v_pk_mul_f32 v[116:117], v[116:117], v[116:117]
	v_exp_f32_e32 v86, v86
	v_exp_f32_e32 v87, v87
	v_add_f32_e32 v96, 1.0, v96
	v_add_f32_e32 v97, 1.0, v97
	v_pk_mul_f32 v[118:119], v[118:119], v[118:119]
	v_sub_f32_e32 v116, 1.0, v116
	v_sub_f32_e32 v117, 1.0, v117
	v_rcp_f32_e32 v96, v96
	v_rcp_f32_e32 v97, v97
	v_add_f32_e32 v98, 1.0, v98
	v_add_f32_e32 v99, 1.0, v99
	v_sqrt_f32_e32 v116, v116
	v_sub_f32_e32 v118, 1.0, v118
	v_sub_f32_e32 v119, 1.0, v119
	v_sqrt_f32_e32 v117, v117
	v_rcp_f32_e32 v98, v98
	v_rcp_f32_e32 v99, v99
	v_sqrt_f32_e32 v118, v118
	v_sqrt_f32_e32 v119, v119
	v_add_f32_e32 v84, 1.0, v84
	v_add_f32_e32 v85, 1.0, v85
	v_rcp_f32_e32 v84, v84
	v_rcp_f32_e32 v85, v85
	v_add_f32_e32 v86, 1.0, v86
	v_add_f32_e32 v87, 1.0, v87
	v_rcp_f32_e32 v86, v86
	v_rcp_f32_e32 v87, v87
	global_store_dwordx4 v[124:125], v[112:115], off offset:16
	v_pk_mul_f32 v[96:97], v[96:97], v[116:117]
	v_lshlrev_b32_e32 v120, 16, v165
	v_lshlrev_b32_e32 v114, 16, v164
	v_and_b32_e32 v115, 0xffff0000, v164
	v_lshlrev_b64 v[112:113], 13, v[206:207]
	v_and_b32_e32 v121, 0xffff0000, v165
	v_pk_mul_f32 v[98:99], v[98:99], v[118:119]
	v_pk_mul_f32 v[96:97], v[96:97], v[114:115]
	v_pk_mul_f32 v[98:99], v[98:99], v[120:121]
	v_cvt_pk_bf16_f32 v96, v104, v96
	v_cvt_pk_bf16_f32 v97, v105, v97
	v_lshl_add_u64 v[104:105], s[92:93], 0, v[112:113]
	v_pk_mul_f32 v[84:85], v[64:65], v[84:85]
	v_cvt_pk_bf16_f32 v98, v106, v98
	v_cvt_pk_bf16_f32 v99, v107, v99
	v_lshl_add_u64 v[104:105], v[104:105], 0, v[196:197]
	v_pk_add_f32 v[76:77], v[76:77], v[72:73]
	v_pk_mul_f32 v[86:87], v[66:67], v[86:87]
	v_pk_mul_f32 v[84:85], v[84:85], s[62:63] op_sel_hi:[1,0]
	v_pk_add_f32 v[60:61], v[60:61], v[100:101]
	global_store_dwordx4 v[104:105], v[96:99], off
	v_pk_add_f32 v[78:79], v[78:79], v[74:75]
	v_mul_f32_e32 v76, 0xbfb8aa3b, v76
	v_mul_f32_e32 v77, 0xbfb8aa3b, v77
	v_pk_mul_f32 v[86:87], v[86:87], s[62:63] op_sel_hi:[1,0]
	v_exp_f32_e32 v98, v84
	v_exp_f32_e32 v99, v85
	v_pk_add_f32 v[62:63], v[62:63], v[102:103]
	v_mul_f32_e32 v60, 0xbfb8aa3b, v60
	v_mul_f32_e32 v61, 0xbfb8aa3b, v61
	v_exp_f32_e32 v76, v76
	v_exp_f32_e32 v77, v77
	v_mul_f32_e32 v78, 0xbfb8aa3b, v78
	v_mul_f32_e32 v79, 0xbfb8aa3b, v79
	v_exp_f32_e32 v106, v86
	v_exp_f32_e32 v107, v87
	v_exp_f32_e32 v60, v60
	v_exp_f32_e32 v61, v61
	v_mul_f32_e32 v62, 0xbfb8aa3b, v62
	v_mul_f32_e32 v63, 0xbfb8aa3b, v63
	v_exp_f32_e32 v78, v78
	v_exp_f32_e32 v79, v79
	v_exp_f32_e32 v62, v62
	v_exp_f32_e32 v63, v63
	v_pk_mul_f32 v[98:99], v[98:99], v[98:99]
	v_add_f32_e32 v76, 1.0, v76
	v_add_f32_e32 v77, 1.0, v77
	v_pk_mul_f32 v[106:107], v[106:107], v[106:107]
	v_sub_f32_e32 v98, 1.0, v98
	v_sub_f32_e32 v99, 1.0, v99
	v_add_f32_e32 v60, 1.0, v60
	v_add_f32_e32 v61, 1.0, v61
	v_rcp_f32_e32 v76, v76
	v_rcp_f32_e32 v77, v77
	v_add_f32_e32 v78, 1.0, v78
	v_add_f32_e32 v79, 1.0, v79
	v_sqrt_f32_e32 v98, v98
	v_sub_f32_e32 v106, 1.0, v106
	v_sub_f32_e32 v107, 1.0, v107
	v_sqrt_f32_e32 v99, v99
	v_rcp_f32_e32 v60, v60
	v_rcp_f32_e32 v61, v61
	v_add_f32_e32 v62, 1.0, v62
	v_add_f32_e32 v63, 1.0, v63
	v_rcp_f32_e32 v78, v78
	v_rcp_f32_e32 v79, v79
	v_sqrt_f32_e32 v106, v106
	v_sqrt_f32_e32 v107, v107
	v_rcp_f32_e32 v62, v62
	v_rcp_f32_e32 v63, v63
	v_lshlrev_b32_e32 v96, 16, v166
	v_and_b32_e32 v97, 0xffff0000, v166
	v_pk_mul_f32 v[76:77], v[76:77], v[98:99]
	v_pk_mul_f32 v[60:61], v[88:89], v[60:61]
	v_lshlrev_b32_e32 v112, 16, v167
	v_and_b32_e32 v113, 0xffff0000, v167
	v_pk_mul_f32 v[78:79], v[78:79], v[106:107]
	v_pk_mul_f32 v[76:77], v[76:77], v[96:97]
	v_pk_add_f32 v[56:57], v[56:57], v[92:93]
	v_pk_mul_f32 v[62:63], v[90:91], v[62:63]
; __device__ __forceinline__ unsigned cvt_pk_bf16(float lo, float hi) { unsigned r; asm volatile("v_cvt_pk_bf16_f32 %0, %1, %2" : "=v"(r) : "v"(lo), "v"(hi)); return r; }
; __device__ __forceinline__ float bf_lo(unsigned w) { return __uint_as_float(w << 16); }
; __device__ __forceinline__ float bf_hi(unsigned w) { return __uint_as_float(w & 0xffff0000u); }
;     __device__ __forceinline__ void operator()(EPI_ARGS) const {
;     ...
;         for (int ai = 0; ai < 2; ++ai)
; #pragma unroll
;             for (int m = 0; m < 4; ++m) {
;                 const int row = ROW_OF(ai, m);
; #pragma unroll
;                 for (int n = 0; n < 2; ++n) {
;                     const unsigned w0 = n ? vv[ai][m].z : vv[ai][m].x, w1 = n ? vv[ai][m].w : vv[ai][m].y;
;                     const f32x4 vx = (f32x4){bf_lo(w0), bf_hi(w0), bf_lo(w1), bf_hi(w1)};
;                     const f32x4 r = sigmoid4(acc[ai][0][m][n] + ba[n]), ig = sigmoid4(acc[ai][1][m][n] + bi[n]);
;                     const f32x4 la = sp[n] * r * (-1.4426950409f);
;                     f32x4 av;
; #pragma unroll
;                     for (int j = 0; j < 4; ++j) av[j] = __builtin_amdgcn_exp2f(la[j]);
;                     const f32x4 om = 1.0f - av * av; f32x4 sq;
; #pragma unroll
;                     for (int j = 0; j < 4; ++j) sq[j] = __builtin_amdgcn_sqrtf(om[j]);
;                     const f32x4 bx = sq * ig * vx;
;                     u32x4 w; w.x = cvt_pk_bf16(la[0], bx[0]); w.y = cvt_pk_bf16(la[1], bx[1]); w.z = cvt_pk_bf16(la[2], bx[2]); w.w = cvt_pk_bf16(la[3], bx[3]);
;                     *(u32x4*)(AB + (size_t)row * LW + c0 + 4 * n) = w;
	v_pk_mul_f32 v[60:61], v[60:61], s[62:63] op_sel_hi:[1,0]
	v_pk_mul_f32 v[78:79], v[78:79], v[112:113]
	v_cvt_pk_bf16_f32 v76, v84, v76
	v_cvt_pk_bf16_f32 v77, v85, v77
	v_pk_add_f32 v[58:59], v[58:59], v[94:95]
	v_mul_f32_e32 v56, 0xbfb8aa3b, v56
	v_mul_f32_e32 v57, 0xbfb8aa3b, v57
	v_pk_mul_f32 v[62:63], v[62:63], s[62:63] op_sel_hi:[1,0]
	v_exp_f32_e32 v84, v60
	v_exp_f32_e32 v85, v61
	v_cvt_pk_bf16_f32 v78, v86, v78
	v_cvt_pk_bf16_f32 v79, v87, v79
	v_exp_f32_e32 v56, v56
	v_exp_f32_e32 v57, v57
	v_mul_f32_e32 v58, 0xbfb8aa3b, v58
	v_mul_f32_e32 v59, 0xbfb8aa3b, v59
	v_exp_f32_e32 v86, v62
	v_exp_f32_e32 v87, v63
	v_pk_add_f32 v[52:53], v[52:53], v[80:81]
	v_exp_f32_e32 v58, v58
	v_exp_f32_e32 v59, v59
	v_pk_add_f32 v[54:55], v[54:55], v[82:83]
	v_mul_f32_e32 v52, 0xbfb8aa3b, v52
	v_mul_f32_e32 v53, 0xbfb8aa3b, v53
	v_exp_f32_e32 v52, v52
	v_exp_f32_e32 v53, v53
	v_mul_f32_e32 v54, 0xbfb8aa3b, v54
	v_mul_f32_e32 v55, 0xbfb8aa3b, v55
	v_pk_mul_f32 v[84:85], v[84:85], v[84:85]
	v_exp_f32_e32 v54, v54
	v_exp_f32_e32 v55, v55
	v_add_f32_e32 v56, 1.0, v56
	v_add_f32_e32 v57, 1.0, v57
	v_pk_mul_f32 v[86:87], v[86:87], v[86:87]
	v_sub_f32_e32 v84, 1.0, v84
	v_sub_f32_e32 v85, 1.0, v85
	v_rcp_f32_e32 v56, v56
	v_rcp_f32_e32 v57, v57
	v_add_f32_e32 v58, 1.0, v58
	v_add_f32_e32 v59, 1.0, v59
	v_sqrt_f32_e32 v84, v84
	v_sub_f32_e32 v86, 1.0, v86
	v_sub_f32_e32 v87, 1.0, v87
	v_sqrt_f32_e32 v85, v85
	v_rcp_f32_e32 v58, v58
	v_rcp_f32_e32 v59, v59
	v_sqrt_f32_e32 v86, v86
	v_sqrt_f32_e32 v87, v87
	v_add_f32_e32 v52, 1.0, v52
	v_add_f32_e32 v53, 1.0, v53
	v_rcp_f32_e32 v52, v52
	v_rcp_f32_e32 v53, v53
	v_add_f32_e32 v54, 1.0, v54
	v_add_f32_e32 v55, 1.0, v55
	v_rcp_f32_e32 v54, v54
	v_rcp_f32_e32 v55, v55
	global_store_dwordx4 v[104:105], v[76:79], off offset:16
	v_pk_mul_f32 v[56:57], v[56:57], v[84:85]
	v_lshlrev_b32_e32 v96, 16, v149
	v_lshlrev_b32_e32 v78, 16, v148
	v_and_b32_e32 v79, 0xffff0000, v148
	v_lshlrev_b64 v[76:77], 13, v[204:205]
	v_and_b32_e32 v97, 0xffff0000, v149
	v_pk_mul_f32 v[58:59], v[58:59], v[86:87]
	v_pk_mul_f32 v[56:57], v[56:57], v[78:79]
	v_pk_mul_f32 v[58:59], v[58:59], v[96:97]
	v_cvt_pk_bf16_f32 v56, v60, v56
	v_cvt_pk_bf16_f32 v57, v61, v57
	v_lshl_add_u64 v[60:61], s[92:93], 0, v[76:77]
	v_pk_mul_f32 v[52:53], v[64:65], v[52:53]
	v_cvt_pk_bf16_f32 v58, v62, v58
	v_cvt_pk_bf16_f32 v59, v63, v59
	v_lshl_add_u64 v[60:61], v[60:61], 0, v[196:197]
	v_pk_add_f32 v[48:49], v[48:49], v[72:73]
	v_pk_mul_f32 v[54:55], v[66:67], v[54:55]
	v_pk_mul_f32 v[52:53], v[52:53], s[62:63] op_sel_hi:[1,0]
	v_pk_add_f32 v[44:45], v[44:45], v[100:101]
	global_store_dwordx4 v[60:61], v[56:59], off
	v_pk_add_f32 v[50:51], v[50:51], v[74:75]
	v_mul_f32_e32 v48, 0xbfb8aa3b, v48
	v_mul_f32_e32 v49, 0xbfb8aa3b, v49
	v_pk_mul_f32 v[54:55], v[54:55], s[62:63] op_sel_hi:[1,0]
	v_exp_f32_e32 v58, v52
	v_exp_f32_e32 v59, v53
	v_pk_add_f32 v[46:47], v[46:47], v[102:103]
	v_mul_f32_e32 v44, 0xbfb8aa3b, v44
	v_mul_f32_e32 v45, 0xbfb8aa3b, v45
	v_exp_f32_e32 v48, v48
	v_exp_f32_e32 v49, v49
	v_mul_f32_e32 v50, 0xbfb8aa3b, v50
	v_mul_f32_e32 v51, 0xbfb8aa3b, v51
	v_exp_f32_e32 v62, v54
	v_exp_f32_e32 v63, v55
	v_exp_f32_e32 v44, v44
	v_exp_f32_e32 v45, v45
	v_mul_f32_e32 v46, 0xbfb8aa3b, v46
	v_mul_f32_e32 v47, 0xbfb8aa3b, v47
	v_exp_f32_e32 v50, v50
	v_exp_f32_e32 v51, v51
	v_exp_f32_e32 v46, v46
	v_exp_f32_e32 v47, v47
	v_pk_mul_f32 v[58:59], v[58:59], v[58:59]
	v_add_f32_e32 v48, 1.0, v48
	v_add_f32_e32 v49, 1.0, v49
	v_pk_mul_f32 v[62:63], v[62:63], v[62:63]
	v_sub_f32_e32 v58, 1.0, v58
	v_sub_f32_e32 v59, 1.0, v59
	v_add_f32_e32 v44, 1.0, v44
	v_add_f32_e32 v45, 1.0, v45
	v_rcp_f32_e32 v48, v48
	v_rcp_f32_e32 v49, v49
	v_add_f32_e32 v50, 1.0, v50
	v_add_f32_e32 v51, 1.0, v51
	v_sqrt_f32_e32 v58, v58
	v_sub_f32_e32 v62, 1.0, v62
	v_sub_f32_e32 v63, 1.0, v63
	v_sqrt_f32_e32 v59, v59
	v_rcp_f32_e32 v44, v44
	v_rcp_f32_e32 v45, v45
	v_add_f32_e32 v46, 1.0, v46
	v_add_f32_e32 v47, 1.0, v47
	v_rcp_f32_e32 v50, v50
	v_rcp_f32_e32 v51, v51
	v_sqrt_f32_e32 v62, v62
	v_sqrt_f32_e32 v63, v63
	v_rcp_f32_e32 v46, v46
	v_rcp_f32_e32 v47, v47
	v_lshlrev_b32_e32 v56, 16, v150
	v_and_b32_e32 v57, 0xffff0000, v150
	v_pk_mul_f32 v[48:49], v[48:49], v[58:59]
	v_pk_mul_f32 v[44:45], v[88:89], v[44:45]
	v_lshlrev_b32_e32 v76, 16, v151
	v_and_b32_e32 v77, 0xffff0000, v151
	v_pk_mul_f32 v[50:51], v[50:51], v[62:63]
	v_pk_mul_f32 v[48:49], v[48:49], v[56:57]
	v_pk_add_f32 v[40:41], v[40:41], v[92:93]
	v_pk_mul_f32 v[46:47], v[90:91], v[46:47]
	v_pk_mul_f32 v[44:45], v[44:45], s[62:63] op_sel_hi:[1,0]
	v_pk_mul_f32 v[50:51], v[50:51], v[76:77]
	v_cvt_pk_bf16_f32 v48, v52, v48
	v_cvt_pk_bf16_f32 v49, v53, v49
	v_pk_add_f32 v[42:43], v[42:43], v[94:95]
	v_mul_f32_e32 v40, 0xbfb8aa3b, v40
	v_mul_f32_e32 v41, 0xbfb8aa3b, v41
	v_pk_mul_f32 v[46:47], v[46:47], s[62:63] op_sel_hi:[1,0]
	v_exp_f32_e32 v52, v44
	v_exp_f32_e32 v53, v45
	v_cvt_pk_bf16_f32 v50, v54, v50
	v_cvt_pk_bf16_f32 v51, v55, v51
	v_exp_f32_e32 v40, v40
	v_exp_f32_e32 v41, v41
	v_mul_f32_e32 v42, 0xbfb8aa3b, v42
	v_mul_f32_e32 v43, 0xbfb8aa3b, v43
	v_exp_f32_e32 v54, v46
	v_exp_f32_e32 v55, v47
	v_pk_add_f32 v[36:37], v[36:37], v[80:81]
	v_exp_f32_e32 v42, v42
	v_exp_f32_e32 v43, v43
	v_pk_add_f32 v[38:39], v[38:39], v[82:83]
	v_mul_f32_e32 v36, 0xbfb8aa3b, v36
	v_mul_f32_e32 v37, 0xbfb8aa3b, v37
	v_exp_f32_e32 v36, v36
	v_exp_f32_e32 v37, v37
	v_mul_f32_e32 v38, 0xbfb8aa3b, v38
	v_mul_f32_e32 v39, 0xbfb8aa3b, v39
	v_pk_mul_f32 v[52:53], v[52:53], v[52:53]
	v_exp_f32_e32 v38, v38
	v_exp_f32_e32 v39, v39
	v_add_f32_e32 v40, 1.0, v40
	v_add_f32_e32 v41, 1.0, v41
	v_pk_mul_f32 v[54:55], v[54:55], v[54:55]
; __device__ __forceinline__ unsigned cvt_pk_bf16(float lo, float hi) { unsigned r; asm volatile("v_cvt_pk_bf16_f32 %0, %1, %2" : "=v"(r) : "v"(lo), "v"(hi)); return r; }
; __device__ __forceinline__ float bf_lo(unsigned w) { return __uint_as_float(w << 16); }
; __device__ __forceinline__ float bf_hi(unsigned w) { return __uint_as_float(w & 0xffff0000u); }
;     __device__ __forceinline__ void operator()(EPI_ARGS) const {
;     ...
;         for (int ai = 0; ai < 2; ++ai)
; #pragma unroll
;             for (int m = 0; m < 4; ++m) {
;                 const int row = ROW_OF(ai, m);
; #pragma unroll
;                 for (int n = 0; n < 2; ++n) {
;                     const unsigned w0 = n ? vv[ai][m].z : vv[ai][m].x, w1 = n ? vv[ai][m].w : vv[ai][m].y;
;                     const f32x4 vx = (f32x4){bf_lo(w0), bf_hi(w0), bf_lo(w1), bf_hi(w1)};
;                     const f32x4 r = sigmoid4(acc[ai][0][m][n] + ba[n]), ig = sigmoid4(acc[ai][1][m][n] + bi[n]);
;                     const f32x4 la = sp[n] * r * (-1.4426950409f);
;                     f32x4 av;
; #pragma unroll
;                     for (int j = 0; j < 4; ++j) av[j] = __builtin_amdgcn_exp2f(la[j]);
;                     const f32x4 om = 1.0f - av * av; f32x4 sq;
; #pragma unroll
;                     for (int j = 0; j < 4; ++j) sq[j] = __builtin_amdgcn_sqrtf(om[j]);
;                     const f32x4 bx = sq * ig * vx;
;                     u32x4 w; w.x = cvt_pk_bf16(la[0], bx[0]); w.y = cvt_pk_bf16(la[1], bx[1]); w.z = cvt_pk_bf16(la[2], bx[2]); w.w = cvt_pk_bf16(la[3], bx[3]);
;                     *(u32x4*)(AB + (size_t)row * LW + c0 + 4 * n) = w;
	v_sub_f32_e32 v52, 1.0, v52
	v_sub_f32_e32 v53, 1.0, v53
	v_rcp_f32_e32 v40, v40
	v_rcp_f32_e32 v41, v41
	v_add_f32_e32 v42, 1.0, v42
	v_add_f32_e32 v43, 1.0, v43
	v_sqrt_f32_e32 v52, v52
	v_sub_f32_e32 v54, 1.0, v54
	v_sub_f32_e32 v55, 1.0, v55
	v_sqrt_f32_e32 v53, v53
	v_rcp_f32_e32 v42, v42
	v_rcp_f32_e32 v43, v43
	v_sqrt_f32_e32 v54, v54
	v_sqrt_f32_e32 v55, v55
	v_add_f32_e32 v36, 1.0, v36
	v_add_f32_e32 v37, 1.0, v37
	v_rcp_f32_e32 v36, v36
	v_rcp_f32_e32 v37, v37
	v_add_f32_e32 v38, 1.0, v38
	v_add_f32_e32 v39, 1.0, v39
	v_rcp_f32_e32 v38, v38
	v_rcp_f32_e32 v39, v39
	global_store_dwordx4 v[60:61], v[48:51], off offset:16
	v_pk_mul_f32 v[40:41], v[40:41], v[52:53]
	v_lshlrev_b32_e32 v56, 16, v129
	v_lshlrev_b32_e32 v50, 16, v128
	v_and_b32_e32 v51, 0xffff0000, v128
	v_lshlrev_b64 v[48:49], 13, v[202:203]
	v_and_b32_e32 v57, 0xffff0000, v129
	v_pk_mul_f32 v[42:43], v[42:43], v[54:55]
	v_pk_mul_f32 v[40:41], v[40:41], v[50:51]
	v_pk_mul_f32 v[42:43], v[42:43], v[56:57]
	v_cvt_pk_bf16_f32 v40, v44, v40
	v_cvt_pk_bf16_f32 v41, v45, v41
	v_lshl_add_u64 v[44:45], s[92:93], 0, v[48:49]
	v_pk_mul_f32 v[36:37], v[64:65], v[36:37]
	v_cvt_pk_bf16_f32 v42, v46, v42
	v_cvt_pk_bf16_f32 v43, v47, v43
	v_lshl_add_u64 v[44:45], v[44:45], 0, v[196:197]
	v_pk_add_f32 v[32:33], v[32:33], v[72:73]
	v_pk_mul_f32 v[38:39], v[66:67], v[38:39]
	v_pk_mul_f32 v[36:37], v[36:37], s[62:63] op_sel_hi:[1,0]
	v_pk_add_f32 v[28:29], v[28:29], v[100:101]
	global_store_dwordx4 v[44:45], v[40:43], off
	v_pk_add_f32 v[34:35], v[34:35], v[74:75]
	v_mul_f32_e32 v32, 0xbfb8aa3b, v32
	v_mul_f32_e32 v33, 0xbfb8aa3b, v33
	v_pk_mul_f32 v[38:39], v[38:39], s[62:63] op_sel_hi:[1,0]
	v_exp_f32_e32 v42, v36
	v_exp_f32_e32 v43, v37
	v_pk_add_f32 v[30:31], v[30:31], v[102:103]
	v_mul_f32_e32 v28, 0xbfb8aa3b, v28
	v_mul_f32_e32 v29, 0xbfb8aa3b, v29
	v_exp_f32_e32 v32, v32
	v_exp_f32_e32 v33, v33
	v_mul_f32_e32 v34, 0xbfb8aa3b, v34
	v_mul_f32_e32 v35, 0xbfb8aa3b, v35
	v_exp_f32_e32 v46, v38
	v_exp_f32_e32 v47, v39
	v_exp_f32_e32 v28, v28
	v_exp_f32_e32 v29, v29
	v_mul_f32_e32 v30, 0xbfb8aa3b, v30
	v_mul_f32_e32 v31, 0xbfb8aa3b, v31
	v_exp_f32_e32 v34, v34
	v_exp_f32_e32 v35, v35
	v_exp_f32_e32 v30, v30
	v_exp_f32_e32 v31, v31
	v_pk_mul_f32 v[42:43], v[42:43], v[42:43]
	v_add_f32_e32 v32, 1.0, v32
	v_add_f32_e32 v33, 1.0, v33
	v_pk_mul_f32 v[46:47], v[46:47], v[46:47]
	v_sub_f32_e32 v42, 1.0, v42
	v_sub_f32_e32 v43, 1.0, v43
	v_add_f32_e32 v28, 1.0, v28
	v_add_f32_e32 v29, 1.0, v29
	v_rcp_f32_e32 v32, v32
	v_rcp_f32_e32 v33, v33
	v_add_f32_e32 v34, 1.0, v34
	v_add_f32_e32 v35, 1.0, v35
	v_sqrt_f32_e32 v42, v42
	v_sub_f32_e32 v46, 1.0, v46
	v_sub_f32_e32 v47, 1.0, v47
	v_sqrt_f32_e32 v43, v43
	v_rcp_f32_e32 v28, v28
	v_rcp_f32_e32 v29, v29
	v_add_f32_e32 v30, 1.0, v30
	v_add_f32_e32 v31, 1.0, v31
	v_rcp_f32_e32 v34, v34
	v_rcp_f32_e32 v35, v35
	v_sqrt_f32_e32 v46, v46
	v_sqrt_f32_e32 v47, v47
	v_rcp_f32_e32 v30, v30
	v_rcp_f32_e32 v31, v31
	v_lshlrev_b32_e32 v40, 16, v130
	v_and_b32_e32 v41, 0xffff0000, v130
	v_pk_mul_f32 v[32:33], v[32:33], v[42:43]
	v_pk_mul_f32 v[28:29], v[88:89], v[28:29]
	v_lshlrev_b32_e32 v48, 16, v131
	v_and_b32_e32 v49, 0xffff0000, v131
	v_pk_mul_f32 v[34:35], v[34:35], v[46:47]
	v_pk_mul_f32 v[32:33], v[32:33], v[40:41]
	v_pk_add_f32 v[24:25], v[24:25], v[92:93]
	v_pk_mul_f32 v[30:31], v[90:91], v[30:31]
	v_pk_mul_f32 v[28:29], v[28:29], s[62:63] op_sel_hi:[1,0]
	v_pk_mul_f32 v[34:35], v[34:35], v[48:49]
	v_cvt_pk_bf16_f32 v32, v36, v32
	v_cvt_pk_bf16_f32 v33, v37, v33
	v_pk_add_f32 v[26:27], v[26:27], v[94:95]
	v_mul_f32_e32 v24, 0xbfb8aa3b, v24
	v_mul_f32_e32 v25, 0xbfb8aa3b, v25
	v_pk_mul_f32 v[30:31], v[30:31], s[62:63] op_sel_hi:[1,0]
	v_exp_f32_e32 v36, v28
	v_exp_f32_e32 v37, v29
	v_cvt_pk_bf16_f32 v34, v38, v34
	v_cvt_pk_bf16_f32 v35, v39, v35
	v_exp_f32_e32 v24, v24
	v_exp_f32_e32 v25, v25
	v_mul_f32_e32 v26, 0xbfb8aa3b, v26
	v_mul_f32_e32 v27, 0xbfb8aa3b, v27
	v_exp_f32_e32 v38, v30
	v_exp_f32_e32 v39, v31
	v_pk_add_f32 v[20:21], v[20:21], v[80:81]
	v_exp_f32_e32 v26, v26
	v_exp_f32_e32 v27, v27
	v_pk_add_f32 v[22:23], v[22:23], v[82:83]
	v_mul_f32_e32 v20, 0xbfb8aa3b, v20
	v_mul_f32_e32 v21, 0xbfb8aa3b, v21
	v_exp_f32_e32 v20, v20
	v_exp_f32_e32 v21, v21
	v_mul_f32_e32 v22, 0xbfb8aa3b, v22
	v_mul_f32_e32 v23, 0xbfb8aa3b, v23
	v_pk_mul_f32 v[36:37], v[36:37], v[36:37]
	v_exp_f32_e32 v22, v22
	v_exp_f32_e32 v23, v23
	v_add_f32_e32 v24, 1.0, v24
	v_add_f32_e32 v25, 1.0, v25
	v_pk_mul_f32 v[38:39], v[38:39], v[38:39]
	v_sub_f32_e32 v36, 1.0, v36
	v_sub_f32_e32 v37, 1.0, v37
	v_rcp_f32_e32 v24, v24
	v_rcp_f32_e32 v25, v25
	v_add_f32_e32 v26, 1.0, v26
	v_add_f32_e32 v27, 1.0, v27
	v_sqrt_f32_e32 v36, v36
	v_sub_f32_e32 v38, 1.0, v38
	v_sub_f32_e32 v39, 1.0, v39
	v_sqrt_f32_e32 v37, v37
	v_rcp_f32_e32 v26, v26
	v_rcp_f32_e32 v27, v27
	v_sqrt_f32_e32 v38, v38
	v_sqrt_f32_e32 v39, v39
	v_add_f32_e32 v20, 1.0, v20
	v_add_f32_e32 v21, 1.0, v21
	v_rcp_f32_e32 v20, v20
	v_rcp_f32_e32 v21, v21
	v_add_f32_e32 v22, 1.0, v22
	v_add_f32_e32 v23, 1.0, v23
	v_rcp_f32_e32 v22, v22
	v_rcp_f32_e32 v23, v23
	global_store_dwordx4 v[44:45], v[32:35], off offset:16
	v_pk_mul_f32 v[24:25], v[24:25], v[36:37]
	v_lshlrev_b32_e32 v40, 16, v109
	v_lshlrev_b32_e32 v34, 16, v108
	v_and_b32_e32 v35, 0xffff0000, v108
	v_lshlrev_b64 v[32:33], 13, v[200:201]
	v_and_b32_e32 v41, 0xffff0000, v109
	v_pk_mul_f32 v[26:27], v[26:27], v[38:39]
	v_pk_mul_f32 v[24:25], v[24:25], v[34:35]
	v_pk_mul_f32 v[26:27], v[26:27], v[40:41]
	v_cvt_pk_bf16_f32 v24, v28, v24
	v_cvt_pk_bf16_f32 v25, v29, v25
	v_lshl_add_u64 v[28:29], s[92:93], 0, v[32:33]
	v_pk_mul_f32 v[20:21], v[64:65], v[20:21]
; __device__ __forceinline__ unsigned cvt_pk_bf16(float lo, float hi) { unsigned r; asm volatile("v_cvt_pk_bf16_f32 %0, %1, %2" : "=v"(r) : "v"(lo), "v"(hi)); return r; }
; __device__ __forceinline__ float bf_lo(unsigned w) { return __uint_as_float(w << 16); }
; __device__ __forceinline__ float bf_hi(unsigned w) { return __uint_as_float(w & 0xffff0000u); }
;     __device__ __forceinline__ void operator()(EPI_ARGS) const {
;     ...
;                 for (int n = 0; n < 2; ++n) {
;                     const unsigned w0 = n ? vv[ai][m].z : vv[ai][m].x, w1 = n ? vv[ai][m].w : vv[ai][m].y;
;                     const f32x4 vx = (f32x4){bf_lo(w0), bf_hi(w0), bf_lo(w1), bf_hi(w1)};
;                     const f32x4 r = sigmoid4(acc[ai][0][m][n] + ba[n]), ig = sigmoid4(acc[ai][1][m][n] + bi[n]);
;                     const f32x4 la = sp[n] * r * (-1.4426950409f);
;                     f32x4 av;
; #pragma unroll
;                     for (int j = 0; j < 4; ++j) av[j] = __builtin_amdgcn_exp2f(la[j]);
;                     const f32x4 om = 1.0f - av * av; f32x4 sq;
; #pragma unroll
;                     for (int j = 0; j < 4; ++j) sq[j] = __builtin_amdgcn_sqrtf(om[j]);
;                     const f32x4 bx = sq * ig * vx;
;                     u32x4 w; w.x = cvt_pk_bf16(la[0], bx[0]); w.y = cvt_pk_bf16(la[1], bx[1]); w.z = cvt_pk_bf16(la[2], bx[2]); w.w = cvt_pk_bf16(la[3], bx[3]);
;                     *(u32x4*)(AB + (size_t)row * LW + c0 + 4 * n) = w;
	v_cvt_pk_bf16_f32 v26, v30, v26
	v_cvt_pk_bf16_f32 v27, v31, v27
	v_lshl_add_u64 v[28:29], v[28:29], 0, v[196:197]
	v_pk_add_f32 v[16:17], v[16:17], v[72:73]
	v_pk_mul_f32 v[22:23], v[66:67], v[22:23]
	v_pk_mul_f32 v[20:21], v[20:21], s[62:63] op_sel_hi:[1,0]
	v_pk_add_f32 v[12:13], v[12:13], v[100:101]
	global_store_dwordx4 v[28:29], v[24:27], off
	v_pk_add_f32 v[18:19], v[18:19], v[74:75]
	v_mul_f32_e32 v16, 0xbfb8aa3b, v16
	v_mul_f32_e32 v17, 0xbfb8aa3b, v17
	v_pk_mul_f32 v[22:23], v[22:23], s[62:63] op_sel_hi:[1,0]
	v_exp_f32_e32 v26, v20
	v_exp_f32_e32 v27, v21
	v_pk_add_f32 v[14:15], v[14:15], v[102:103]
	v_mul_f32_e32 v12, 0xbfb8aa3b, v12
	v_mul_f32_e32 v13, 0xbfb8aa3b, v13
	v_exp_f32_e32 v16, v16
	v_exp_f32_e32 v17, v17
	v_mul_f32_e32 v18, 0xbfb8aa3b, v18
	v_mul_f32_e32 v19, 0xbfb8aa3b, v19
	v_exp_f32_e32 v30, v22
	v_exp_f32_e32 v31, v23
	v_exp_f32_e32 v12, v12
	v_exp_f32_e32 v13, v13
	v_mul_f32_e32 v14, 0xbfb8aa3b, v14
	v_mul_f32_e32 v15, 0xbfb8aa3b, v15
	v_exp_f32_e32 v18, v18
	v_exp_f32_e32 v19, v19
	v_exp_f32_e32 v14, v14
	v_exp_f32_e32 v15, v15
	v_pk_mul_f32 v[26:27], v[26:27], v[26:27]
	v_add_f32_e32 v16, 1.0, v16
	v_add_f32_e32 v17, 1.0, v17
	v_pk_mul_f32 v[30:31], v[30:31], v[30:31]
	v_sub_f32_e32 v26, 1.0, v26
	v_sub_f32_e32 v27, 1.0, v27
	v_add_f32_e32 v12, 1.0, v12
	v_add_f32_e32 v13, 1.0, v13
	v_rcp_f32_e32 v16, v16
	v_rcp_f32_e32 v17, v17
	v_add_f32_e32 v18, 1.0, v18
	v_add_f32_e32 v19, 1.0, v19
	v_sqrt_f32_e32 v26, v26
	v_sub_f32_e32 v30, 1.0, v30
	v_sub_f32_e32 v31, 1.0, v31
	v_sqrt_f32_e32 v27, v27
	v_rcp_f32_e32 v12, v12
	v_rcp_f32_e32 v13, v13
	v_add_f32_e32 v14, 1.0, v14
	v_add_f32_e32 v15, 1.0, v15
	v_rcp_f32_e32 v18, v18
	v_rcp_f32_e32 v19, v19
	v_sqrt_f32_e32 v30, v30
	v_sqrt_f32_e32 v31, v31
	v_rcp_f32_e32 v14, v14
	v_rcp_f32_e32 v15, v15
	v_lshlrev_b32_e32 v24, 16, v110
	v_and_b32_e32 v25, 0xffff0000, v110
	v_pk_mul_f32 v[16:17], v[16:17], v[26:27]
	v_pk_mul_f32 v[12:13], v[88:89], v[12:13]
	v_lshlrev_b32_e32 v32, 16, v111
	v_and_b32_e32 v33, 0xffff0000, v111
	v_pk_mul_f32 v[18:19], v[18:19], v[30:31]
	v_pk_mul_f32 v[16:17], v[16:17], v[24:25]
	v_pk_add_f32 v[8:9], v[8:9], v[92:93]
	v_pk_mul_f32 v[14:15], v[90:91], v[14:15]
	v_pk_mul_f32 v[12:13], v[12:13], s[62:63] op_sel_hi:[1,0]
	v_pk_mul_f32 v[18:19], v[18:19], v[32:33]
	v_cvt_pk_bf16_f32 v16, v20, v16
	v_cvt_pk_bf16_f32 v17, v21, v17
	v_pk_add_f32 v[10:11], v[10:11], v[94:95]
	v_mul_f32_e32 v8, 0xbfb8aa3b, v8
	v_mul_f32_e32 v9, 0xbfb8aa3b, v9
	v_pk_mul_f32 v[14:15], v[14:15], s[62:63] op_sel_hi:[1,0]
	v_exp_f32_e32 v20, v12
	v_exp_f32_e32 v21, v13
	v_cvt_pk_bf16_f32 v18, v22, v18
	v_cvt_pk_bf16_f32 v19, v23, v19
	v_exp_f32_e32 v8, v8
	v_exp_f32_e32 v9, v9
	v_mul_f32_e32 v10, 0xbfb8aa3b, v10
	v_mul_f32_e32 v11, 0xbfb8aa3b, v11
	v_exp_f32_e32 v22, v14
	v_exp_f32_e32 v23, v15
	v_pk_add_f32 v[6:7], v[6:7], v[82:83]
	v_pk_add_f32 v[4:5], v[4:5], v[80:81]
	v_exp_f32_e32 v10, v10
	v_exp_f32_e32 v11, v11
	v_mul_f32_e32 v4, 0xbfb8aa3b, v4
	v_mul_f32_e32 v5, 0xbfb8aa3b, v5
	v_mul_f32_e32 v6, 0xbfb8aa3b, v6
	v_mul_f32_e32 v7, 0xbfb8aa3b, v7
	v_exp_f32_e32 v4, v4
	v_exp_f32_e32 v5, v5
	v_exp_f32_e32 v6, v6
	v_exp_f32_e32 v7, v7
	v_pk_mul_f32 v[20:21], v[20:21], v[20:21]
	v_add_f32_e32 v8, 1.0, v8
	v_add_f32_e32 v9, 1.0, v9
	v_pk_mul_f32 v[22:23], v[22:23], v[22:23]
	v_sub_f32_e32 v20, 1.0, v20
	v_sub_f32_e32 v21, 1.0, v21
	v_rcp_f32_e32 v8, v8
	v_rcp_f32_e32 v9, v9
	v_add_f32_e32 v10, 1.0, v10
	v_add_f32_e32 v11, 1.0, v11
	v_sqrt_f32_e32 v20, v20
	v_sub_f32_e32 v22, 1.0, v22
	v_sub_f32_e32 v23, 1.0, v23
	v_sqrt_f32_e32 v21, v21
	v_rcp_f32_e32 v10, v10
	v_rcp_f32_e32 v11, v11
	v_sqrt_f32_e32 v22, v22
	v_sqrt_f32_e32 v23, v23
	v_add_f32_e32 v4, 1.0, v4
	v_add_f32_e32 v5, 1.0, v5
	v_add_f32_e32 v6, 1.0, v6
	v_add_f32_e32 v7, 1.0, v7
	v_rcp_f32_e32 v4, v4
	v_rcp_f32_e32 v5, v5
	v_rcp_f32_e32 v6, v6
	v_rcp_f32_e32 v7, v7
	global_store_dwordx4 v[28:29], v[16:19], off offset:16
	v_pk_mul_f32 v[8:9], v[8:9], v[20:21]
	v_lshlrev_b32_e32 v24, 16, v69
	v_lshlrev_b32_e32 v18, 16, v68
	v_and_b32_e32 v19, 0xffff0000, v68
	v_lshlrev_b64 v[16:17], 13, v[198:199]
	v_and_b32_e32 v25, 0xffff0000, v69
	v_pk_mul_f32 v[10:11], v[10:11], v[22:23]
	v_pk_mul_f32 v[8:9], v[8:9], v[18:19]
	v_pk_mul_f32 v[10:11], v[10:11], v[24:25]
	v_cvt_pk_bf16_f32 v8, v12, v8
	v_cvt_pk_bf16_f32 v9, v13, v9
	v_lshl_add_u64 v[12:13], s[92:93], 0, v[16:17]
	v_pk_mul_f32 v[6:7], v[66:67], v[6:7]
	v_pk_mul_f32 v[4:5], v[64:65], v[4:5]
	v_cvt_pk_bf16_f32 v10, v14, v10
	v_cvt_pk_bf16_f32 v11, v15, v11
	v_lshl_add_u64 v[12:13], v[12:13], 0, v[196:197]
	v_pk_add_f32 v[2:3], v[2:3], v[74:75]
	v_pk_add_f32 v[0:1], v[0:1], v[72:73]
	v_pk_mul_f32 v[6:7], v[6:7], s[62:63] op_sel_hi:[1,0]
	v_pk_mul_f32 v[4:5], v[4:5], s[62:63] op_sel_hi:[1,0]
	global_store_dwordx4 v[12:13], v[8:11], off
	v_mul_f32_e32 v0, 0xbfb8aa3b, v0
	v_mul_f32_e32 v1, 0xbfb8aa3b, v1
	v_mul_f32_e32 v2, 0xbfb8aa3b, v2
	v_mul_f32_e32 v3, 0xbfb8aa3b, v3
	v_exp_f32_e32 v10, v4
	v_exp_f32_e32 v14, v6
	v_exp_f32_e32 v15, v7
	v_exp_f32_e32 v11, v5
	v_exp_f32_e32 v0, v0
	v_exp_f32_e32 v1, v1
	v_exp_f32_e32 v2, v2
	v_exp_f32_e32 v3, v3
	v_pk_mul_f32 v[14:15], v[14:15], v[14:15]
	v_pk_mul_f32 v[10:11], v[10:11], v[10:11]
	v_add_f32_e32 v0, 1.0, v0
	v_add_f32_e32 v1, 1.0, v1
	v_add_f32_e32 v2, 1.0, v2
	v_add_f32_e32 v3, 1.0, v3
	v_sub_f32_e32 v10, 1.0, v10
	v_sub_f32_e32 v11, 1.0, v11
	v_sub_f32_e32 v14, 1.0, v14
	v_sub_f32_e32 v15, 1.0, v15
	v_rcp_f32_e32 v0, v0
	v_rcp_f32_e32 v1, v1
	v_rcp_f32_e32 v2, v2
	v_rcp_f32_e32 v3, v3
	v_sqrt_f32_e32 v10, v10
	v_sqrt_f32_e32 v14, v14
	v_sqrt_f32_e32 v15, v15
	v_sqrt_f32_e32 v11, v11
	v_lshlrev_b32_e32 v8, 16, v70
	v_and_b32_e32 v9, 0xffff0000, v70
	v_lshlrev_b32_e32 v16, 16, v71
	v_and_b32_e32 v17, 0xffff0000, v71
	v_pk_mul_f32 v[2:3], v[2:3], v[14:15]
	v_pk_mul_f32 v[0:1], v[0:1], v[10:11]
	v_pk_mul_f32 v[2:3], v[2:3], v[16:17]
	v_pk_mul_f32 v[0:1], v[0:1], v[8:9]
	s_nop 0
	v_cvt_pk_bf16_f32 v0, v4, v0
	v_cvt_pk_bf16_f32 v1, v5, v1
	v_cvt_pk_bf16_f32 v2, v6, v2
	v_cvt_pk_bf16_f32 v3, v7, v3
	global_store_dwordx4 v[12:13], v[0:3], off offset:16
	s_mov_b64 s[4:5], vcc
	s_waitcnt vmcnt(0)
	s_barrier
; __device__ __forceinline__ float bf_lo(unsigned w) { return __uint_as_float(w << 16); }
; __device__ __forceinline__ float bf_hi(unsigned w) { return __uint_as_float(w & 0xffff0000u); }
; __global__ void __launch_bounds__(NTHR, 2) hybrid_block_fwd(Args a) {
;     ...
;         const int c2 = gtid & 1023, chunk = (gtid >> 10) & (NCH - 1), b = gtid >> 16;
;         const size_t r0 = (size_t)b * SEQ + (size_t)chunk * CH_L;
;         const u32x2* pab = (const u32x2*)((const unsigned*)AF + r0 * LW) + c2;
;         f32x2 P = (f32x2){1.f, 1.f}, H = (f32x2){0.f, 0.f};
; #pragma unroll 32
;         for (int i = 0; i < CH_L; ++i) { const u32x2 q = pab[(size_t)i * (LW / 2)];
;             const f32x2 av = (f32x2){__builtin_amdgcn_exp2f(bf_lo(q.x)), __builtin_amdgcn_exp2f(bf_lo(q.y))}, bv = (f32x2){bf_hi(q.x), bf_hi(q.y)}; P = P * av; H = av * H + bv; }
;         ((f32x2*)(AGGP + (size_t)(b * NCH + chunk) * LW))[c2] = P; ((f32x2*)(AGGH + (size_t)(b * NCH + chunk) * LW))[c2] = H;
	v_cmp_gt_u32_e32 vcc, 0x100, v212
	s_and_saveexec_b64 s[22:23], vcc
	s_cbranch_execz .Lp2b_agg_skip
	v_lshrrev_b32_e32 v1, 7, v212
	v_and_b32_e32 v2, 0x7f, v212
	s_lshl_b32 s32, s74, 8
	s_lshl_b32 s45, s27, 7
	s_lshl_b32 s63, s74, 1
	v_lshl_add_u32 v3, v1, 7, s32
	v_lshlrev_b32_e32 v3, 13, v3
	v_add_u32_e32 v4, s45, v2
	v_lshl_add_u32 v3, v4, 2, v3
	v_add_u32_e32 v7, s63, v1
	v_lshl_add_u32 v7, v7, 11, v4
	v_lshlrev_b32_e32 v7, 2, v7
	v_add_u32_e32 v10, 0x100000, v7
	s_mov_b64 s[76:77], s[92:93]
	s_add_u32 s78, s94, 0x100000
	s_addc_u32 s79, s95, 0
	global_load_dword v32, v3, s[76:77]
	s_add_u32 s76, s76, 0x2000
	s_addc_u32 s77, s77, 0
	global_load_dword v33, v3, s[76:77]
	s_add_u32 s76, s76, 0x2000
	s_addc_u32 s77, s77, 0
	global_load_dword v34, v3, s[76:77]
	s_add_u32 s76, s76, 0x2000
	s_addc_u32 s77, s77, 0
	global_load_dword v35, v3, s[76:77]
	s_add_u32 s76, s76, 0x2000
	s_addc_u32 s77, s77, 0
	global_load_dword v36, v3, s[76:77]
	s_add_u32 s76, s76, 0x2000
	s_addc_u32 s77, s77, 0
	global_load_dword v37, v3, s[76:77]
	s_add_u32 s76, s76, 0x2000
	s_addc_u32 s77, s77, 0
	global_load_dword v38, v3, s[76:77]
	s_add_u32 s76, s76, 0x2000
	s_addc_u32 s77, s77, 0
	global_load_dword v39, v3, s[76:77]
	s_add_u32 s76, s76, 0x2000
	s_addc_u32 s77, s77, 0
	global_load_dword v40, v3, s[76:77]
	s_add_u32 s76, s76, 0x2000
	s_addc_u32 s77, s77, 0
	global_load_dword v41, v3, s[76:77]
	s_add_u32 s76, s76, 0x2000
	s_addc_u32 s77, s77, 0
	global_load_dword v42, v3, s[76:77]
	s_add_u32 s76, s76, 0x2000
	s_addc_u32 s77, s77, 0
	global_load_dword v43, v3, s[76:77]
	s_add_u32 s76, s76, 0x2000
	s_addc_u32 s77, s77, 0
	global_load_dword v44, v3, s[76:77]
	s_add_u32 s76, s76, 0x2000
	s_addc_u32 s77, s77, 0
	global_load_dword v45, v3, s[76:77]
	s_add_u32 s76, s76, 0x2000
	s_addc_u32 s77, s77, 0
	global_load_dword v46, v3, s[76:77]
	s_add_u32 s76, s76, 0x2000
	s_addc_u32 s77, s77, 0
	global_load_dword v47, v3, s[76:77]
	s_add_u32 s76, s76, 0x2000
	s_addc_u32 s77, s77, 0
	global_load_dword v48, v3, s[76:77]
	s_add_u32 s76, s76, 0x2000
	s_addc_u32 s77, s77, 0
	global_load_dword v49, v3, s[76:77]
	s_add_u32 s76, s76, 0x2000
	s_addc_u32 s77, s77, 0
	global_load_dword v50, v3, s[76:77]
	s_add_u32 s76, s76, 0x2000
	s_addc_u32 s77, s77, 0
	global_load_dword v51, v3, s[76:77]
	s_add_u32 s76, s76, 0x2000
	s_addc_u32 s77, s77, 0
	global_load_dword v52, v3, s[76:77]
	s_add_u32 s76, s76, 0x2000
	s_addc_u32 s77, s77, 0
	global_load_dword v53, v3, s[76:77]
	s_add_u32 s76, s76, 0x2000
	s_addc_u32 s77, s77, 0
	global_load_dword v54, v3, s[76:77]
	s_add_u32 s76, s76, 0x2000
	s_addc_u32 s77, s77, 0
	global_load_dword v55, v3, s[76:77]
	s_add_u32 s76, s76, 0x2000
	s_addc_u32 s77, s77, 0
	global_load_dword v56, v3, s[76:77]
	s_add_u32 s76, s76, 0x2000
	s_addc_u32 s77, s77, 0
	global_load_dword v57, v3, s[76:77]
	s_add_u32 s76, s76, 0x2000
	s_addc_u32 s77, s77, 0
	global_load_dword v58, v3, s[76:77]
	s_add_u32 s76, s76, 0x2000
	s_addc_u32 s77, s77, 0
	global_load_dword v59, v3, s[76:77]
	s_add_u32 s76, s76, 0x2000
	s_addc_u32 s77, s77, 0
	global_load_dword v60, v3, s[76:77]
	s_add_u32 s76, s76, 0x2000
	s_addc_u32 s77, s77, 0
	global_load_dword v61, v3, s[76:77]
	s_add_u32 s76, s76, 0x2000
	s_addc_u32 s77, s77, 0
	global_load_dword v62, v3, s[76:77]
	s_add_u32 s76, s76, 0x2000
	s_addc_u32 s77, s77, 0
	global_load_dword v63, v3, s[76:77]
	s_add_u32 s76, s76, 0x2000
	s_addc_u32 s77, s77, 0
	v_mov_b32_e32 v5, 1.0
	v_mov_b32_e32 v6, 0
	s_waitcnt vmcnt(31)
	v_lshlrev_b32_e32 v8, 16, v32
	v_and_b32_e32 v9, 0xffff0000, v32
	v_exp_f32_e32 v8, v8
	global_load_dword v32, v3, s[76:77]
	s_add_u32 s76, s76, 0x2000
	s_addc_u32 s77, s77, 0
	v_mul_f32_e32 v5, v5, v8
	v_fma_f32 v6, v6, v8, v9
	s_waitcnt vmcnt(31)
	v_lshlrev_b32_e32 v11, 16, v33
	v_and_b32_e32 v12, 0xffff0000, v33
	v_exp_f32_e32 v11, v11
	global_load_dword v33, v3, s[76:77]
	s_add_u32 s76, s76, 0x2000
	s_addc_u32 s77, s77, 0
	v_mul_f32_e32 v5, v5, v11
	v_fma_f32 v6, v6, v11, v12
	s_waitcnt vmcnt(31)
	v_lshlrev_b32_e32 v8, 16, v34
	v_and_b32_e32 v9, 0xffff0000, v34
	v_exp_f32_e32 v8, v8
	global_load_dword v34, v3, s[76:77]
	s_add_u32 s76, s76, 0x2000
	s_addc_u32 s77, s77, 0
	v_mul_f32_e32 v5, v5, v8
	v_fma_f32 v6, v6, v8, v9
	s_waitcnt vmcnt(31)
	v_lshlrev_b32_e32 v11, 16, v35
	v_and_b32_e32 v12, 0xffff0000, v35
	v_exp_f32_e32 v11, v11
	global_load_dword v35, v3, s[76:77]
	s_add_u32 s76, s76, 0x2000
	s_addc_u32 s77, s77, 0
	v_mul_f32_e32 v5, v5, v11
	v_fma_f32 v6, v6, v11, v12
	s_waitcnt vmcnt(31)
	v_lshlrev_b32_e32 v8, 16, v36
	v_and_b32_e32 v9, 0xffff0000, v36
	v_exp_f32_e32 v8, v8
	global_load_dword v36, v3, s[76:77]
	s_add_u32 s76, s76, 0x2000
	s_addc_u32 s77, s77, 0
	v_mul_f32_e32 v5, v5, v8
	v_fma_f32 v6, v6, v8, v9
	s_waitcnt vmcnt(31)
	v_lshlrev_b32_e32 v11, 16, v37
	v_and_b32_e32 v12, 0xffff0000, v37
	v_exp_f32_e32 v11, v11
	global_load_dword v37, v3, s[76:77]
	s_add_u32 s76, s76, 0x2000
	s_addc_u32 s77, s77, 0
	v_mul_f32_e32 v5, v5, v11
	v_fma_f32 v6, v6, v11, v12
	s_waitcnt vmcnt(31)
	v_lshlrev_b32_e32 v8, 16, v38
	v_and_b32_e32 v9, 0xffff0000, v38
	v_exp_f32_e32 v8, v8
	global_load_dword v38, v3, s[76:77]
	s_add_u32 s76, s76, 0x2000
	s_addc_u32 s77, s77, 0
	v_mul_f32_e32 v5, v5, v8
	v_fma_f32 v6, v6, v8, v9
	s_waitcnt vmcnt(31)
	v_lshlrev_b32_e32 v11, 16, v39
	v_and_b32_e32 v12, 0xffff0000, v39
	v_exp_f32_e32 v11, v11
	global_load_dword v39, v3, s[76:77]
	s_add_u32 s76, s76, 0x2000
	s_addc_u32 s77, s77, 0
	v_mul_f32_e32 v5, v5, v11
	v_fma_f32 v6, v6, v11, v12
	s_waitcnt vmcnt(31)
	v_lshlrev_b32_e32 v8, 16, v40
	v_and_b32_e32 v9, 0xffff0000, v40
	v_exp_f32_e32 v8, v8
	global_load_dword v40, v3, s[76:77]
	s_add_u32 s76, s76, 0x2000
	s_addc_u32 s77, s77, 0
	v_mul_f32_e32 v5, v5, v8
	v_fma_f32 v6, v6, v8, v9
	s_waitcnt vmcnt(31)
; __device__ __forceinline__ float bf_lo(unsigned w) { return __uint_as_float(w << 16); }
; __device__ __forceinline__ float bf_hi(unsigned w) { return __uint_as_float(w & 0xffff0000u); }
; __global__ void __launch_bounds__(NTHR, 2) hybrid_block_fwd(Args a) {
;     ...
;         for (int i = 0; i < CH_L; ++i) { const u32x2 q = pab[(size_t)i * (LW / 2)];
;             const f32x2 av = (f32x2){__builtin_amdgcn_exp2f(bf_lo(q.x)), __builtin_amdgcn_exp2f(bf_lo(q.y))}, bv = (f32x2){bf_hi(q.x), bf_hi(q.y)}; P = P * av; H = av * H + bv; }
	v_lshlrev_b32_e32 v11, 16, v41
	v_and_b32_e32 v12, 0xffff0000, v41
	v_exp_f32_e32 v11, v11
	global_load_dword v41, v3, s[76:77]
	s_add_u32 s76, s76, 0x2000
	s_addc_u32 s77, s77, 0
	v_mul_f32_e32 v5, v5, v11
	v_fma_f32 v6, v6, v11, v12
	s_waitcnt vmcnt(31)
	v_lshlrev_b32_e32 v8, 16, v42
	v_and_b32_e32 v9, 0xffff0000, v42
	v_exp_f32_e32 v8, v8
	global_load_dword v42, v3, s[76:77]
	s_add_u32 s76, s76, 0x2000
	s_addc_u32 s77, s77, 0
	v_mul_f32_e32 v5, v5, v8
	v_fma_f32 v6, v6, v8, v9
	s_waitcnt vmcnt(31)
	v_lshlrev_b32_e32 v11, 16, v43
	v_and_b32_e32 v12, 0xffff0000, v43
	v_exp_f32_e32 v11, v11
	global_load_dword v43, v3, s[76:77]
	s_add_u32 s76, s76, 0x2000
	s_addc_u32 s77, s77, 0
	v_mul_f32_e32 v5, v5, v11
	v_fma_f32 v6, v6, v11, v12
	s_waitcnt vmcnt(31)
	v_lshlrev_b32_e32 v8, 16, v44
	v_and_b32_e32 v9, 0xffff0000, v44
	v_exp_f32_e32 v8, v8
	global_load_dword v44, v3, s[76:77]
	s_add_u32 s76, s76, 0x2000
	s_addc_u32 s77, s77, 0
	v_mul_f32_e32 v5, v5, v8
	v_fma_f32 v6, v6, v8, v9
	s_waitcnt vmcnt(31)
	v_lshlrev_b32_e32 v11, 16, v45
	v_and_b32_e32 v12, 0xffff0000, v45
	v_exp_f32_e32 v11, v11
	global_load_dword v45, v3, s[76:77]
	s_add_u32 s76, s76, 0x2000
	s_addc_u32 s77, s77, 0
	v_mul_f32_e32 v5, v5, v11
	v_fma_f32 v6, v6, v11, v12
	s_waitcnt vmcnt(31)
	v_lshlrev_b32_e32 v8, 16, v46
	v_and_b32_e32 v9, 0xffff0000, v46
	v_exp_f32_e32 v8, v8
	global_load_dword v46, v3, s[76:77]
	s_add_u32 s76, s76, 0x2000
	s_addc_u32 s77, s77, 0
	v_mul_f32_e32 v5, v5, v8
	v_fma_f32 v6, v6, v8, v9
	s_waitcnt vmcnt(31)
	v_lshlrev_b32_e32 v11, 16, v47
	v_and_b32_e32 v12, 0xffff0000, v47
	v_exp_f32_e32 v11, v11
	global_load_dword v47, v3, s[76:77]
	s_add_u32 s76, s76, 0x2000
	s_addc_u32 s77, s77, 0
	v_mul_f32_e32 v5, v5, v11
	v_fma_f32 v6, v6, v11, v12
	s_waitcnt vmcnt(31)
	v_lshlrev_b32_e32 v8, 16, v48
	v_and_b32_e32 v9, 0xffff0000, v48
	v_exp_f32_e32 v8, v8
	global_load_dword v48, v3, s[76:77]
	s_add_u32 s76, s76, 0x2000
	s_addc_u32 s77, s77, 0
	v_mul_f32_e32 v5, v5, v8
	v_fma_f32 v6, v6, v8, v9
	s_waitcnt vmcnt(31)
	v_lshlrev_b32_e32 v11, 16, v49
	v_and_b32_e32 v12, 0xffff0000, v49
	v_exp_f32_e32 v11, v11
	global_load_dword v49, v3, s[76:77]
	s_add_u32 s76, s76, 0x2000
	s_addc_u32 s77, s77, 0
	v_mul_f32_e32 v5, v5, v11
	v_fma_f32 v6, v6, v11, v12
	s_waitcnt vmcnt(31)
	v_lshlrev_b32_e32 v8, 16, v50
	v_and_b32_e32 v9, 0xffff0000, v50
	v_exp_f32_e32 v8, v8
	global_load_dword v50, v3, s[76:77]
	s_add_u32 s76, s76, 0x2000
	s_addc_u32 s77, s77, 0
	v_mul_f32_e32 v5, v5, v8
	v_fma_f32 v6, v6, v8, v9
	s_waitcnt vmcnt(31)
	v_lshlrev_b32_e32 v11, 16, v51
	v_and_b32_e32 v12, 0xffff0000, v51
	v_exp_f32_e32 v11, v11
	global_load_dword v51, v3, s[76:77]
	s_add_u32 s76, s76, 0x2000
	s_addc_u32 s77, s77, 0
	v_mul_f32_e32 v5, v5, v11
	v_fma_f32 v6, v6, v11, v12
	s_waitcnt vmcnt(31)
	v_lshlrev_b32_e32 v8, 16, v52
	v_and_b32_e32 v9, 0xffff0000, v52
	v_exp_f32_e32 v8, v8
	global_load_dword v52, v3, s[76:77]
	s_add_u32 s76, s76, 0x2000
	s_addc_u32 s77, s77, 0
	v_mul_f32_e32 v5, v5, v8
	v_fma_f32 v6, v6, v8, v9
	s_waitcnt vmcnt(31)
	v_lshlrev_b32_e32 v11, 16, v53
	v_and_b32_e32 v12, 0xffff0000, v53
	v_exp_f32_e32 v11, v11
	global_load_dword v53, v3, s[76:77]
	s_add_u32 s76, s76, 0x2000
	s_addc_u32 s77, s77, 0
	v_mul_f32_e32 v5, v5, v11
	v_fma_f32 v6, v6, v11, v12
	s_waitcnt vmcnt(31)
	v_lshlrev_b32_e32 v8, 16, v54
	v_and_b32_e32 v9, 0xffff0000, v54
	v_exp_f32_e32 v8, v8
	global_load_dword v54, v3, s[76:77]
	s_add_u32 s76, s76, 0x2000
	s_addc_u32 s77, s77, 0
	v_mul_f32_e32 v5, v5, v8
	v_fma_f32 v6, v6, v8, v9
	s_waitcnt vmcnt(31)
	v_lshlrev_b32_e32 v11, 16, v55
	v_and_b32_e32 v12, 0xffff0000, v55
	v_exp_f32_e32 v11, v11
	global_load_dword v55, v3, s[76:77]
	s_add_u32 s76, s76, 0x2000
	s_addc_u32 s77, s77, 0
	v_mul_f32_e32 v5, v5, v11
	v_fma_f32 v6, v6, v11, v12
	s_waitcnt vmcnt(31)
	v_lshlrev_b32_e32 v8, 16, v56
	v_and_b32_e32 v9, 0xffff0000, v56
	v_exp_f32_e32 v8, v8
	global_load_dword v56, v3, s[76:77]
	s_add_u32 s76, s76, 0x2000
	s_addc_u32 s77, s77, 0
	v_mul_f32_e32 v5, v5, v8
	v_fma_f32 v6, v6, v8, v9
	s_waitcnt vmcnt(31)
	v_lshlrev_b32_e32 v11, 16, v57
	v_and_b32_e32 v12, 0xffff0000, v57
	v_exp_f32_e32 v11, v11
	global_load_dword v57, v3, s[76:77]
	s_add_u32 s76, s76, 0x2000
	s_addc_u32 s77, s77, 0
	v_mul_f32_e32 v5, v5, v11
	v_fma_f32 v6, v6, v11, v12
	s_waitcnt vmcnt(31)
	v_lshlrev_b32_e32 v8, 16, v58
	v_and_b32_e32 v9, 0xffff0000, v58
	v_exp_f32_e32 v8, v8
	global_load_dword v58, v3, s[76:77]
	s_add_u32 s76, s76, 0x2000
	s_addc_u32 s77, s77, 0
	v_mul_f32_e32 v5, v5, v8
	v_fma_f32 v6, v6, v8, v9
	s_waitcnt vmcnt(31)
	v_lshlrev_b32_e32 v11, 16, v59
	v_and_b32_e32 v12, 0xffff0000, v59
	v_exp_f32_e32 v11, v11
	global_load_dword v59, v3, s[76:77]
	s_add_u32 s76, s76, 0x2000
	s_addc_u32 s77, s77, 0
	v_mul_f32_e32 v5, v5, v11
	v_fma_f32 v6, v6, v11, v12
	s_waitcnt vmcnt(31)
	v_lshlrev_b32_e32 v8, 16, v60
	v_and_b32_e32 v9, 0xffff0000, v60
	v_exp_f32_e32 v8, v8
	global_load_dword v60, v3, s[76:77]
	s_add_u32 s76, s76, 0x2000
	s_addc_u32 s77, s77, 0
	v_mul_f32_e32 v5, v5, v8
	v_fma_f32 v6, v6, v8, v9
	s_waitcnt vmcnt(31)
	v_lshlrev_b32_e32 v11, 16, v61
	v_and_b32_e32 v12, 0xffff0000, v61
	v_exp_f32_e32 v11, v11
	global_load_dword v61, v3, s[76:77]
	s_add_u32 s76, s76, 0x2000
	s_addc_u32 s77, s77, 0
	v_mul_f32_e32 v5, v5, v11
	v_fma_f32 v6, v6, v11, v12
	s_waitcnt vmcnt(31)
	v_lshlrev_b32_e32 v8, 16, v62
	v_and_b32_e32 v9, 0xffff0000, v62
	v_exp_f32_e32 v8, v8
	global_load_dword v62, v3, s[76:77]
	s_add_u32 s76, s76, 0x2000
	s_addc_u32 s77, s77, 0
	v_mul_f32_e32 v5, v5, v8
	v_fma_f32 v6, v6, v8, v9
	s_waitcnt vmcnt(31)
; __device__ __forceinline__ float bf_lo(unsigned w) { return __uint_as_float(w << 16); }
; __device__ __forceinline__ float bf_hi(unsigned w) { return __uint_as_float(w & 0xffff0000u); }
; __global__ void __launch_bounds__(NTHR, 2) hybrid_block_fwd(Args a) {
;     ...
;         for (int i = 0; i < CH_L; ++i) { const u32x2 q = pab[(size_t)i * (LW / 2)];
;             const f32x2 av = (f32x2){__builtin_amdgcn_exp2f(bf_lo(q.x)), __builtin_amdgcn_exp2f(bf_lo(q.y))}, bv = (f32x2){bf_hi(q.x), bf_hi(q.y)}; P = P * av; H = av * H + bv; }
	v_lshlrev_b32_e32 v11, 16, v63
	v_and_b32_e32 v12, 0xffff0000, v63
	v_exp_f32_e32 v11, v11
	global_load_dword v63, v3, s[76:77]
	s_add_u32 s76, s76, 0x2000
	s_addc_u32 s77, s77, 0
	v_mul_f32_e32 v5, v5, v11
	v_fma_f32 v6, v6, v11, v12
	s_waitcnt vmcnt(31)
	v_lshlrev_b32_e32 v8, 16, v32
	v_and_b32_e32 v9, 0xffff0000, v32
	v_exp_f32_e32 v8, v8
	global_load_dword v32, v3, s[76:77]
	s_add_u32 s76, s76, 0x2000
	s_addc_u32 s77, s77, 0
	v_mul_f32_e32 v5, v5, v8
	v_fma_f32 v6, v6, v8, v9
	s_waitcnt vmcnt(31)
	v_lshlrev_b32_e32 v11, 16, v33
	v_and_b32_e32 v12, 0xffff0000, v33
	v_exp_f32_e32 v11, v11
	global_load_dword v33, v3, s[76:77]
	s_add_u32 s76, s76, 0x2000
	s_addc_u32 s77, s77, 0
	v_mul_f32_e32 v5, v5, v11
	v_fma_f32 v6, v6, v11, v12
	s_waitcnt vmcnt(31)
	v_lshlrev_b32_e32 v8, 16, v34
	v_and_b32_e32 v9, 0xffff0000, v34
	v_exp_f32_e32 v8, v8
	global_load_dword v34, v3, s[76:77]
	s_add_u32 s76, s76, 0x2000
	s_addc_u32 s77, s77, 0
	v_mul_f32_e32 v5, v5, v8
	v_fma_f32 v6, v6, v8, v9
	s_waitcnt vmcnt(31)
	v_lshlrev_b32_e32 v11, 16, v35
	v_and_b32_e32 v12, 0xffff0000, v35
	v_exp_f32_e32 v11, v11
	global_load_dword v35, v3, s[76:77]
	s_add_u32 s76, s76, 0x2000
	s_addc_u32 s77, s77, 0
	v_mul_f32_e32 v5, v5, v11
	v_fma_f32 v6, v6, v11, v12
	s_waitcnt vmcnt(31)
	v_lshlrev_b32_e32 v8, 16, v36
	v_and_b32_e32 v9, 0xffff0000, v36
	v_exp_f32_e32 v8, v8
	global_load_dword v36, v3, s[76:77]
	s_add_u32 s76, s76, 0x2000
	s_addc_u32 s77, s77, 0
	v_mul_f32_e32 v5, v5, v8
	v_fma_f32 v6, v6, v8, v9
	s_waitcnt vmcnt(31)
	v_lshlrev_b32_e32 v11, 16, v37
	v_and_b32_e32 v12, 0xffff0000, v37
	v_exp_f32_e32 v11, v11
	global_load_dword v37, v3, s[76:77]
	s_add_u32 s76, s76, 0x2000
	s_addc_u32 s77, s77, 0
	v_mul_f32_e32 v5, v5, v11
	v_fma_f32 v6, v6, v11, v12
	s_waitcnt vmcnt(31)
	v_lshlrev_b32_e32 v8, 16, v38
	v_and_b32_e32 v9, 0xffff0000, v38
	v_exp_f32_e32 v8, v8
	global_load_dword v38, v3, s[76:77]
	s_add_u32 s76, s76, 0x2000
	s_addc_u32 s77, s77, 0
	v_mul_f32_e32 v5, v5, v8
	v_fma_f32 v6, v6, v8, v9
	s_waitcnt vmcnt(31)
	v_lshlrev_b32_e32 v11, 16, v39
	v_and_b32_e32 v12, 0xffff0000, v39
	v_exp_f32_e32 v11, v11
	global_load_dword v39, v3, s[76:77]
	s_add_u32 s76, s76, 0x2000
	s_addc_u32 s77, s77, 0
	v_mul_f32_e32 v5, v5, v11
	v_fma_f32 v6, v6, v11, v12
	s_waitcnt vmcnt(31)
	v_lshlrev_b32_e32 v8, 16, v40
	v_and_b32_e32 v9, 0xffff0000, v40
	v_exp_f32_e32 v8, v8
	global_load_dword v40, v3, s[76:77]
	s_add_u32 s76, s76, 0x2000
	s_addc_u32 s77, s77, 0
	v_mul_f32_e32 v5, v5, v8
	v_fma_f32 v6, v6, v8, v9
	s_waitcnt vmcnt(31)
	v_lshlrev_b32_e32 v11, 16, v41
	v_and_b32_e32 v12, 0xffff0000, v41
	v_exp_f32_e32 v11, v11
	global_load_dword v41, v3, s[76:77]
	s_add_u32 s76, s76, 0x2000
	s_addc_u32 s77, s77, 0
	v_mul_f32_e32 v5, v5, v11
	v_fma_f32 v6, v6, v11, v12
	s_waitcnt vmcnt(31)
	v_lshlrev_b32_e32 v8, 16, v42
	v_and_b32_e32 v9, 0xffff0000, v42
	v_exp_f32_e32 v8, v8
	global_load_dword v42, v3, s[76:77]
	s_add_u32 s76, s76, 0x2000
	s_addc_u32 s77, s77, 0
	v_mul_f32_e32 v5, v5, v8
	v_fma_f32 v6, v6, v8, v9
	s_waitcnt vmcnt(31)
	v_lshlrev_b32_e32 v11, 16, v43
	v_and_b32_e32 v12, 0xffff0000, v43
	v_exp_f32_e32 v11, v11
	global_load_dword v43, v3, s[76:77]
	s_add_u32 s76, s76, 0x2000
	s_addc_u32 s77, s77, 0
	v_mul_f32_e32 v5, v5, v11
	v_fma_f32 v6, v6, v11, v12
	s_waitcnt vmcnt(31)
	v_lshlrev_b32_e32 v8, 16, v44
	v_and_b32_e32 v9, 0xffff0000, v44
	v_exp_f32_e32 v8, v8
	global_load_dword v44, v3, s[76:77]
	s_add_u32 s76, s76, 0x2000
	s_addc_u32 s77, s77, 0
	v_mul_f32_e32 v5, v5, v8
	v_fma_f32 v6, v6, v8, v9
	s_waitcnt vmcnt(31)
	v_lshlrev_b32_e32 v11, 16, v45
	v_and_b32_e32 v12, 0xffff0000, v45
	v_exp_f32_e32 v11, v11
	global_load_dword v45, v3, s[76:77]
	s_add_u32 s76, s76, 0x2000
	s_addc_u32 s77, s77, 0
	v_mul_f32_e32 v5, v5, v11
	v_fma_f32 v6, v6, v11, v12
	s_waitcnt vmcnt(31)
	v_lshlrev_b32_e32 v8, 16, v46
	v_and_b32_e32 v9, 0xffff0000, v46
	v_exp_f32_e32 v8, v8
	global_load_dword v46, v3, s[76:77]
	s_add_u32 s76, s76, 0x2000
	s_addc_u32 s77, s77, 0
	v_mul_f32_e32 v5, v5, v8
	v_fma_f32 v6, v6, v8, v9
	s_waitcnt vmcnt(31)
	v_lshlrev_b32_e32 v11, 16, v47
	v_and_b32_e32 v12, 0xffff0000, v47
	v_exp_f32_e32 v11, v11
	global_load_dword v47, v3, s[76:77]
	s_add_u32 s76, s76, 0x2000
	s_addc_u32 s77, s77, 0
	v_mul_f32_e32 v5, v5, v11
	v_fma_f32 v6, v6, v11, v12
	s_waitcnt vmcnt(31)
	v_lshlrev_b32_e32 v8, 16, v48
	v_and_b32_e32 v9, 0xffff0000, v48
	v_exp_f32_e32 v8, v8
	global_load_dword v48, v3, s[76:77]
	s_add_u32 s76, s76, 0x2000
	s_addc_u32 s77, s77, 0
	v_mul_f32_e32 v5, v5, v8
	v_fma_f32 v6, v6, v8, v9
	s_waitcnt vmcnt(31)
	v_lshlrev_b32_e32 v11, 16, v49
	v_and_b32_e32 v12, 0xffff0000, v49
	v_exp_f32_e32 v11, v11
	global_load_dword v49, v3, s[76:77]
	s_add_u32 s76, s76, 0x2000
	s_addc_u32 s77, s77, 0
	v_mul_f32_e32 v5, v5, v11
	v_fma_f32 v6, v6, v11, v12
	s_waitcnt vmcnt(31)
	v_lshlrev_b32_e32 v8, 16, v50
	v_and_b32_e32 v9, 0xffff0000, v50
	v_exp_f32_e32 v8, v8
	global_load_dword v50, v3, s[76:77]
	s_add_u32 s76, s76, 0x2000
	s_addc_u32 s77, s77, 0
	v_mul_f32_e32 v5, v5, v8
	v_fma_f32 v6, v6, v8, v9
	s_waitcnt vmcnt(31)
	v_lshlrev_b32_e32 v11, 16, v51
	v_and_b32_e32 v12, 0xffff0000, v51
	v_exp_f32_e32 v11, v11
	global_load_dword v51, v3, s[76:77]
	s_add_u32 s76, s76, 0x2000
	s_addc_u32 s77, s77, 0
	v_mul_f32_e32 v5, v5, v11
	v_fma_f32 v6, v6, v11, v12
	s_waitcnt vmcnt(31)
	v_lshlrev_b32_e32 v8, 16, v52
	v_and_b32_e32 v9, 0xffff0000, v52
	v_exp_f32_e32 v8, v8
	global_load_dword v52, v3, s[76:77]
	s_add_u32 s76, s76, 0x2000
	s_addc_u32 s77, s77, 0
	v_mul_f32_e32 v5, v5, v8
	v_fma_f32 v6, v6, v8, v9
	s_waitcnt vmcnt(31)
; __device__ __forceinline__ float bf_lo(unsigned w) { return __uint_as_float(w << 16); }
; __device__ __forceinline__ float bf_hi(unsigned w) { return __uint_as_float(w & 0xffff0000u); }
; __global__ void __launch_bounds__(NTHR, 2) hybrid_block_fwd(Args a) {
;     ...
;         for (int i = 0; i < CH_L; ++i) { const u32x2 q = pab[(size_t)i * (LW / 2)];
;             const f32x2 av = (f32x2){__builtin_amdgcn_exp2f(bf_lo(q.x)), __builtin_amdgcn_exp2f(bf_lo(q.y))}, bv = (f32x2){bf_hi(q.x), bf_hi(q.y)}; P = P * av; H = av * H + bv; }
	v_lshlrev_b32_e32 v11, 16, v53
	v_and_b32_e32 v12, 0xffff0000, v53
	v_exp_f32_e32 v11, v11
	global_load_dword v53, v3, s[76:77]
	s_add_u32 s76, s76, 0x2000
	s_addc_u32 s77, s77, 0
	v_mul_f32_e32 v5, v5, v11
	v_fma_f32 v6, v6, v11, v12
	s_waitcnt vmcnt(31)
	v_lshlrev_b32_e32 v8, 16, v54
	v_and_b32_e32 v9, 0xffff0000, v54
	v_exp_f32_e32 v8, v8
	global_load_dword v54, v3, s[76:77]
	s_add_u32 s76, s76, 0x2000
	s_addc_u32 s77, s77, 0
	v_mul_f32_e32 v5, v5, v8
	v_fma_f32 v6, v6, v8, v9
	s_waitcnt vmcnt(31)
	v_lshlrev_b32_e32 v11, 16, v55
	v_and_b32_e32 v12, 0xffff0000, v55
	v_exp_f32_e32 v11, v11
	global_load_dword v55, v3, s[76:77]
	s_add_u32 s76, s76, 0x2000
	s_addc_u32 s77, s77, 0
	v_mul_f32_e32 v5, v5, v11
	v_fma_f32 v6, v6, v11, v12
	s_waitcnt vmcnt(31)
	v_lshlrev_b32_e32 v8, 16, v56
	v_and_b32_e32 v9, 0xffff0000, v56
	v_exp_f32_e32 v8, v8
	global_load_dword v56, v3, s[76:77]
	s_add_u32 s76, s76, 0x2000
	s_addc_u32 s77, s77, 0
	v_mul_f32_e32 v5, v5, v8
	v_fma_f32 v6, v6, v8, v9
	s_waitcnt vmcnt(31)
	v_lshlrev_b32_e32 v11, 16, v57
	v_and_b32_e32 v12, 0xffff0000, v57
	v_exp_f32_e32 v11, v11
	global_load_dword v57, v3, s[76:77]
	s_add_u32 s76, s76, 0x2000
	s_addc_u32 s77, s77, 0
	v_mul_f32_e32 v5, v5, v11
	v_fma_f32 v6, v6, v11, v12
	s_waitcnt vmcnt(31)
	v_lshlrev_b32_e32 v8, 16, v58
	v_and_b32_e32 v9, 0xffff0000, v58
	v_exp_f32_e32 v8, v8
	global_load_dword v58, v3, s[76:77]
	s_add_u32 s76, s76, 0x2000
	s_addc_u32 s77, s77, 0
	v_mul_f32_e32 v5, v5, v8
	v_fma_f32 v6, v6, v8, v9
	s_waitcnt vmcnt(31)
	v_lshlrev_b32_e32 v11, 16, v59
	v_and_b32_e32 v12, 0xffff0000, v59
	v_exp_f32_e32 v11, v11
	global_load_dword v59, v3, s[76:77]
	s_add_u32 s76, s76, 0x2000
	s_addc_u32 s77, s77, 0
	v_mul_f32_e32 v5, v5, v11
	v_fma_f32 v6, v6, v11, v12
	s_waitcnt vmcnt(31)
	v_lshlrev_b32_e32 v8, 16, v60
	v_and_b32_e32 v9, 0xffff0000, v60
	v_exp_f32_e32 v8, v8
	global_load_dword v60, v3, s[76:77]
	s_add_u32 s76, s76, 0x2000
	s_addc_u32 s77, s77, 0
	v_mul_f32_e32 v5, v5, v8
	v_fma_f32 v6, v6, v8, v9
	s_waitcnt vmcnt(31)
	v_lshlrev_b32_e32 v11, 16, v61
	v_and_b32_e32 v12, 0xffff0000, v61
	v_exp_f32_e32 v11, v11
	global_load_dword v61, v3, s[76:77]
	s_add_u32 s76, s76, 0x2000
	s_addc_u32 s77, s77, 0
	v_mul_f32_e32 v5, v5, v11
	v_fma_f32 v6, v6, v11, v12
	s_waitcnt vmcnt(31)
	v_lshlrev_b32_e32 v8, 16, v62
	v_and_b32_e32 v9, 0xffff0000, v62
	v_exp_f32_e32 v8, v8
	global_load_dword v62, v3, s[76:77]
	s_add_u32 s76, s76, 0x2000
	s_addc_u32 s77, s77, 0
	v_mul_f32_e32 v5, v5, v8
	v_fma_f32 v6, v6, v8, v9
	s_waitcnt vmcnt(31)
	v_lshlrev_b32_e32 v11, 16, v63
	v_and_b32_e32 v12, 0xffff0000, v63
	v_exp_f32_e32 v11, v11
	global_load_dword v63, v3, s[76:77]
	s_add_u32 s76, s76, 0x2000
	s_addc_u32 s77, s77, 0
	v_mul_f32_e32 v5, v5, v11
	v_fma_f32 v6, v6, v11, v12
	s_waitcnt vmcnt(31)
	v_lshlrev_b32_e32 v8, 16, v32
	v_and_b32_e32 v9, 0xffff0000, v32
	v_exp_f32_e32 v8, v8
	global_load_dword v32, v3, s[76:77]
	s_add_u32 s76, s76, 0x2000
	s_addc_u32 s77, s77, 0
	v_mul_f32_e32 v5, v5, v8
	v_fma_f32 v6, v6, v8, v9
	s_waitcnt vmcnt(31)
	v_lshlrev_b32_e32 v11, 16, v33
	v_and_b32_e32 v12, 0xffff0000, v33
	v_exp_f32_e32 v11, v11
	global_load_dword v33, v3, s[76:77]
	s_add_u32 s76, s76, 0x2000
	s_addc_u32 s77, s77, 0
	v_mul_f32_e32 v5, v5, v11
	v_fma_f32 v6, v6, v11, v12
	s_waitcnt vmcnt(31)
	v_lshlrev_b32_e32 v8, 16, v34
	v_and_b32_e32 v9, 0xffff0000, v34
	v_exp_f32_e32 v8, v8
	global_load_dword v34, v3, s[76:77]
	s_add_u32 s76, s76, 0x2000
	s_addc_u32 s77, s77, 0
	v_mul_f32_e32 v5, v5, v8
	v_fma_f32 v6, v6, v8, v9
	s_waitcnt vmcnt(31)
	v_lshlrev_b32_e32 v11, 16, v35
	v_and_b32_e32 v12, 0xffff0000, v35
	v_exp_f32_e32 v11, v11
	global_load_dword v35, v3, s[76:77]
	s_add_u32 s76, s76, 0x2000
	s_addc_u32 s77, s77, 0
	v_mul_f32_e32 v5, v5, v11
	v_fma_f32 v6, v6, v11, v12
	s_waitcnt vmcnt(31)
	v_lshlrev_b32_e32 v8, 16, v36
	v_and_b32_e32 v9, 0xffff0000, v36
	v_exp_f32_e32 v8, v8
	global_load_dword v36, v3, s[76:77]
	s_add_u32 s76, s76, 0x2000
	s_addc_u32 s77, s77, 0
	v_mul_f32_e32 v5, v5, v8
	v_fma_f32 v6, v6, v8, v9
	s_waitcnt vmcnt(31)
	v_lshlrev_b32_e32 v11, 16, v37
	v_and_b32_e32 v12, 0xffff0000, v37
	v_exp_f32_e32 v11, v11
	global_load_dword v37, v3, s[76:77]
	s_add_u32 s76, s76, 0x2000
	s_addc_u32 s77, s77, 0
	v_mul_f32_e32 v5, v5, v11
	v_fma_f32 v6, v6, v11, v12
	s_waitcnt vmcnt(31)
	v_lshlrev_b32_e32 v8, 16, v38
	v_and_b32_e32 v9, 0xffff0000, v38
	v_exp_f32_e32 v8, v8
	global_load_dword v38, v3, s[76:77]
	s_add_u32 s76, s76, 0x2000
	s_addc_u32 s77, s77, 0
	v_mul_f32_e32 v5, v5, v8
	v_fma_f32 v6, v6, v8, v9
	s_waitcnt vmcnt(31)
	v_lshlrev_b32_e32 v11, 16, v39
	v_and_b32_e32 v12, 0xffff0000, v39
	v_exp_f32_e32 v11, v11
	global_load_dword v39, v3, s[76:77]
	s_add_u32 s76, s76, 0x2000
	s_addc_u32 s77, s77, 0
	v_mul_f32_e32 v5, v5, v11
	v_fma_f32 v6, v6, v11, v12
	s_waitcnt vmcnt(31)
	v_lshlrev_b32_e32 v8, 16, v40
	v_and_b32_e32 v9, 0xffff0000, v40
	v_exp_f32_e32 v8, v8
	global_load_dword v40, v3, s[76:77]
	s_add_u32 s76, s76, 0x2000
	s_addc_u32 s77, s77, 0
	v_mul_f32_e32 v5, v5, v8
	v_fma_f32 v6, v6, v8, v9
	s_waitcnt vmcnt(31)
	v_lshlrev_b32_e32 v11, 16, v41
	v_and_b32_e32 v12, 0xffff0000, v41
	v_exp_f32_e32 v11, v11
	global_load_dword v41, v3, s[76:77]
	s_add_u32 s76, s76, 0x2000
	s_addc_u32 s77, s77, 0
	v_mul_f32_e32 v5, v5, v11
	v_fma_f32 v6, v6, v11, v12
	s_waitcnt vmcnt(31)
	v_lshlrev_b32_e32 v8, 16, v42
	v_and_b32_e32 v9, 0xffff0000, v42
	v_exp_f32_e32 v8, v8
	global_load_dword v42, v3, s[76:77]
	s_add_u32 s76, s76, 0x2000
	s_addc_u32 s77, s77, 0
	v_mul_f32_e32 v5, v5, v8
	v_fma_f32 v6, v6, v8, v9
	s_waitcnt vmcnt(31)
; __device__ __forceinline__ float bf_lo(unsigned w) { return __uint_as_float(w << 16); }
; __device__ __forceinline__ float bf_hi(unsigned w) { return __uint_as_float(w & 0xffff0000u); }
; __global__ void __launch_bounds__(NTHR, 2) hybrid_block_fwd(Args a) {
;     ...
;         for (int i = 0; i < CH_L; ++i) { const u32x2 q = pab[(size_t)i * (LW / 2)];
;             const f32x2 av = (f32x2){__builtin_amdgcn_exp2f(bf_lo(q.x)), __builtin_amdgcn_exp2f(bf_lo(q.y))}, bv = (f32x2){bf_hi(q.x), bf_hi(q.y)}; P = P * av; H = av * H + bv; }
	v_lshlrev_b32_e32 v11, 16, v43
	v_and_b32_e32 v12, 0xffff0000, v43
	v_exp_f32_e32 v11, v11
	global_load_dword v43, v3, s[76:77]
	s_add_u32 s76, s76, 0x2000
	s_addc_u32 s77, s77, 0
	v_mul_f32_e32 v5, v5, v11
	v_fma_f32 v6, v6, v11, v12
	s_waitcnt vmcnt(31)
	v_lshlrev_b32_e32 v8, 16, v44
	v_and_b32_e32 v9, 0xffff0000, v44
	v_exp_f32_e32 v8, v8
	global_load_dword v44, v3, s[76:77]
	s_add_u32 s76, s76, 0x2000
	s_addc_u32 s77, s77, 0
	v_mul_f32_e32 v5, v5, v8
	v_fma_f32 v6, v6, v8, v9
	s_waitcnt vmcnt(31)
	v_lshlrev_b32_e32 v11, 16, v45
	v_and_b32_e32 v12, 0xffff0000, v45
	v_exp_f32_e32 v11, v11
	global_load_dword v45, v3, s[76:77]
	s_add_u32 s76, s76, 0x2000
	s_addc_u32 s77, s77, 0
	v_mul_f32_e32 v5, v5, v11
	v_fma_f32 v6, v6, v11, v12
	s_waitcnt vmcnt(31)
	v_lshlrev_b32_e32 v8, 16, v46
	v_and_b32_e32 v9, 0xffff0000, v46
	v_exp_f32_e32 v8, v8
	global_load_dword v46, v3, s[76:77]
	s_add_u32 s76, s76, 0x2000
	s_addc_u32 s77, s77, 0
	v_mul_f32_e32 v5, v5, v8
	v_fma_f32 v6, v6, v8, v9
	s_waitcnt vmcnt(31)
	v_lshlrev_b32_e32 v11, 16, v47
	v_and_b32_e32 v12, 0xffff0000, v47
	v_exp_f32_e32 v11, v11
	global_load_dword v47, v3, s[76:77]
	s_add_u32 s76, s76, 0x2000
	s_addc_u32 s77, s77, 0
	v_mul_f32_e32 v5, v5, v11
	v_fma_f32 v6, v6, v11, v12
	s_waitcnt vmcnt(31)
	v_lshlrev_b32_e32 v8, 16, v48
	v_and_b32_e32 v9, 0xffff0000, v48
	v_exp_f32_e32 v8, v8
	global_load_dword v48, v3, s[76:77]
	s_add_u32 s76, s76, 0x2000
	s_addc_u32 s77, s77, 0
	v_mul_f32_e32 v5, v5, v8
	v_fma_f32 v6, v6, v8, v9
	s_waitcnt vmcnt(31)
	v_lshlrev_b32_e32 v11, 16, v49
	v_and_b32_e32 v12, 0xffff0000, v49
	v_exp_f32_e32 v11, v11
	global_load_dword v49, v3, s[76:77]
	s_add_u32 s76, s76, 0x2000
	s_addc_u32 s77, s77, 0
	v_mul_f32_e32 v5, v5, v11
	v_fma_f32 v6, v6, v11, v12
	s_waitcnt vmcnt(31)
	v_lshlrev_b32_e32 v8, 16, v50
	v_and_b32_e32 v9, 0xffff0000, v50
	v_exp_f32_e32 v8, v8
	global_load_dword v50, v3, s[76:77]
	s_add_u32 s76, s76, 0x2000
	s_addc_u32 s77, s77, 0
	v_mul_f32_e32 v5, v5, v8
	v_fma_f32 v6, v6, v8, v9
	s_waitcnt vmcnt(31)
	v_lshlrev_b32_e32 v11, 16, v51
	v_and_b32_e32 v12, 0xffff0000, v51
	v_exp_f32_e32 v11, v11
	global_load_dword v51, v3, s[76:77]
	s_add_u32 s76, s76, 0x2000
	s_addc_u32 s77, s77, 0
	v_mul_f32_e32 v5, v5, v11
	v_fma_f32 v6, v6, v11, v12
	s_waitcnt vmcnt(31)
	v_lshlrev_b32_e32 v8, 16, v52
	v_and_b32_e32 v9, 0xffff0000, v52
	v_exp_f32_e32 v8, v8
	global_load_dword v52, v3, s[76:77]
	s_add_u32 s76, s76, 0x2000
	s_addc_u32 s77, s77, 0
	v_mul_f32_e32 v5, v5, v8
	v_fma_f32 v6, v6, v8, v9
	s_waitcnt vmcnt(31)
	v_lshlrev_b32_e32 v11, 16, v53
	v_and_b32_e32 v12, 0xffff0000, v53
	v_exp_f32_e32 v11, v11
	global_load_dword v53, v3, s[76:77]
	s_add_u32 s76, s76, 0x2000
	s_addc_u32 s77, s77, 0
	v_mul_f32_e32 v5, v5, v11
	v_fma_f32 v6, v6, v11, v12
	s_waitcnt vmcnt(31)
	v_lshlrev_b32_e32 v8, 16, v54
	v_and_b32_e32 v9, 0xffff0000, v54
	v_exp_f32_e32 v8, v8
	global_load_dword v54, v3, s[76:77]
	s_add_u32 s76, s76, 0x2000
	s_addc_u32 s77, s77, 0
	v_mul_f32_e32 v5, v5, v8
	v_fma_f32 v6, v6, v8, v9
	s_waitcnt vmcnt(31)
	v_lshlrev_b32_e32 v11, 16, v55
	v_and_b32_e32 v12, 0xffff0000, v55
	v_exp_f32_e32 v11, v11
	global_load_dword v55, v3, s[76:77]
	s_add_u32 s76, s76, 0x2000
	s_addc_u32 s77, s77, 0
	v_mul_f32_e32 v5, v5, v11
	v_fma_f32 v6, v6, v11, v12
	s_waitcnt vmcnt(31)
	v_lshlrev_b32_e32 v8, 16, v56
	v_and_b32_e32 v9, 0xffff0000, v56
	v_exp_f32_e32 v8, v8
	global_load_dword v56, v3, s[76:77]
	s_add_u32 s76, s76, 0x2000
	s_addc_u32 s77, s77, 0
	v_mul_f32_e32 v5, v5, v8
	v_fma_f32 v6, v6, v8, v9
	s_waitcnt vmcnt(31)
	v_lshlrev_b32_e32 v11, 16, v57
	v_and_b32_e32 v12, 0xffff0000, v57
	v_exp_f32_e32 v11, v11
	global_load_dword v57, v3, s[76:77]
	s_add_u32 s76, s76, 0x2000
	s_addc_u32 s77, s77, 0
	v_mul_f32_e32 v5, v5, v11
	v_fma_f32 v6, v6, v11, v12
	s_waitcnt vmcnt(31)
	v_lshlrev_b32_e32 v8, 16, v58
	v_and_b32_e32 v9, 0xffff0000, v58
	v_exp_f32_e32 v8, v8
	global_load_dword v58, v3, s[76:77]
	s_add_u32 s76, s76, 0x2000
	s_addc_u32 s77, s77, 0
	v_mul_f32_e32 v5, v5, v8
	v_fma_f32 v6, v6, v8, v9
	s_waitcnt vmcnt(31)
	v_lshlrev_b32_e32 v11, 16, v59
	v_and_b32_e32 v12, 0xffff0000, v59
	v_exp_f32_e32 v11, v11
	global_load_dword v59, v3, s[76:77]
	s_add_u32 s76, s76, 0x2000
	s_addc_u32 s77, s77, 0
	v_mul_f32_e32 v5, v5, v11
	v_fma_f32 v6, v6, v11, v12
	s_waitcnt vmcnt(31)
	v_lshlrev_b32_e32 v8, 16, v60
	v_and_b32_e32 v9, 0xffff0000, v60
	v_exp_f32_e32 v8, v8
	global_load_dword v60, v3, s[76:77]
	s_add_u32 s76, s76, 0x2000
	s_addc_u32 s77, s77, 0
	v_mul_f32_e32 v5, v5, v8
	v_fma_f32 v6, v6, v8, v9
	s_waitcnt vmcnt(31)
	v_lshlrev_b32_e32 v11, 16, v61
	v_and_b32_e32 v12, 0xffff0000, v61
	v_exp_f32_e32 v11, v11
	global_load_dword v61, v3, s[76:77]
	s_add_u32 s76, s76, 0x2000
	s_addc_u32 s77, s77, 0
	v_mul_f32_e32 v5, v5, v11
	v_fma_f32 v6, v6, v11, v12
	s_waitcnt vmcnt(31)
	v_lshlrev_b32_e32 v8, 16, v62
	v_and_b32_e32 v9, 0xffff0000, v62
	v_exp_f32_e32 v8, v8
	global_load_dword v62, v3, s[76:77]
	s_add_u32 s76, s76, 0x2000
	s_addc_u32 s77, s77, 0
	v_mul_f32_e32 v5, v5, v8
	v_fma_f32 v6, v6, v8, v9
	s_waitcnt vmcnt(31)
	v_lshlrev_b32_e32 v11, 16, v63
	v_and_b32_e32 v12, 0xffff0000, v63
	v_exp_f32_e32 v11, v11
	global_load_dword v63, v3, s[76:77]
	s_add_u32 s76, s76, 0x2000
	s_addc_u32 s77, s77, 0
	v_mul_f32_e32 v5, v5, v11
	v_fma_f32 v6, v6, v11, v12
	s_waitcnt vmcnt(31)
	v_lshlrev_b32_e32 v8, 16, v32
	v_and_b32_e32 v9, 0xffff0000, v32
	v_exp_f32_e32 v8, v8
	s_nop 0
	v_mul_f32_e32 v5, v5, v8
	v_fma_f32 v6, v6, v8, v9
	s_waitcnt vmcnt(30)
; __device__ __forceinline__ float bf_lo(unsigned w) { return __uint_as_float(w << 16); }
; __device__ __forceinline__ float bf_hi(unsigned w) { return __uint_as_float(w & 0xffff0000u); }
; __global__ void __launch_bounds__(NTHR, 2) hybrid_block_fwd(Args a) {
;     ...
;         for (int i = 0; i < CH_L; ++i) { const u32x2 q = pab[(size_t)i * (LW / 2)];
;             const f32x2 av = (f32x2){__builtin_amdgcn_exp2f(bf_lo(q.x)), __builtin_amdgcn_exp2f(bf_lo(q.y))}, bv = (f32x2){bf_hi(q.x), bf_hi(q.y)}; P = P * av; H = av * H + bv; }
;         ((f32x2*)(AGGP + (size_t)(b * NCH + chunk) * LW))[c2] = P; ((f32x2*)(AGGH + (size_t)(b * NCH + chunk) * LW))[c2] = H;
	v_lshlrev_b32_e32 v11, 16, v33
	v_and_b32_e32 v12, 0xffff0000, v33
	v_exp_f32_e32 v11, v11
	s_nop 0
	v_mul_f32_e32 v5, v5, v11
	v_fma_f32 v6, v6, v11, v12
	s_waitcnt vmcnt(29)
	v_lshlrev_b32_e32 v8, 16, v34
	v_and_b32_e32 v9, 0xffff0000, v34
	v_exp_f32_e32 v8, v8
	s_nop 0
	v_mul_f32_e32 v5, v5, v8
	v_fma_f32 v6, v6, v8, v9
	s_waitcnt vmcnt(28)
	v_lshlrev_b32_e32 v11, 16, v35
	v_and_b32_e32 v12, 0xffff0000, v35
	v_exp_f32_e32 v11, v11
	s_nop 0
	v_mul_f32_e32 v5, v5, v11
	v_fma_f32 v6, v6, v11, v12
	s_waitcnt vmcnt(27)
	v_lshlrev_b32_e32 v8, 16, v36
	v_and_b32_e32 v9, 0xffff0000, v36
	v_exp_f32_e32 v8, v8
	s_nop 0
	v_mul_f32_e32 v5, v5, v8
	v_fma_f32 v6, v6, v8, v9
	s_waitcnt vmcnt(26)
	v_lshlrev_b32_e32 v11, 16, v37
	v_and_b32_e32 v12, 0xffff0000, v37
	v_exp_f32_e32 v11, v11
	s_nop 0
	v_mul_f32_e32 v5, v5, v11
	v_fma_f32 v6, v6, v11, v12
	s_waitcnt vmcnt(25)
	v_lshlrev_b32_e32 v8, 16, v38
	v_and_b32_e32 v9, 0xffff0000, v38
	v_exp_f32_e32 v8, v8
	s_nop 0
	v_mul_f32_e32 v5, v5, v8
	v_fma_f32 v6, v6, v8, v9
	s_waitcnt vmcnt(24)
	v_lshlrev_b32_e32 v11, 16, v39
	v_and_b32_e32 v12, 0xffff0000, v39
	v_exp_f32_e32 v11, v11
	s_nop 0
	v_mul_f32_e32 v5, v5, v11
	v_fma_f32 v6, v6, v11, v12
	s_waitcnt vmcnt(23)
	v_lshlrev_b32_e32 v8, 16, v40
	v_and_b32_e32 v9, 0xffff0000, v40
	v_exp_f32_e32 v8, v8
	s_nop 0
	v_mul_f32_e32 v5, v5, v8
	v_fma_f32 v6, v6, v8, v9
	s_waitcnt vmcnt(22)
	v_lshlrev_b32_e32 v11, 16, v41
	v_and_b32_e32 v12, 0xffff0000, v41
	v_exp_f32_e32 v11, v11
	s_nop 0
	v_mul_f32_e32 v5, v5, v11
	v_fma_f32 v6, v6, v11, v12
	s_waitcnt vmcnt(21)
	v_lshlrev_b32_e32 v8, 16, v42
	v_and_b32_e32 v9, 0xffff0000, v42
	v_exp_f32_e32 v8, v8
	s_nop 0
	v_mul_f32_e32 v5, v5, v8
	v_fma_f32 v6, v6, v8, v9
	s_waitcnt vmcnt(20)
	v_lshlrev_b32_e32 v11, 16, v43
	v_and_b32_e32 v12, 0xffff0000, v43
	v_exp_f32_e32 v11, v11
	s_nop 0
	v_mul_f32_e32 v5, v5, v11
	v_fma_f32 v6, v6, v11, v12
	s_waitcnt vmcnt(19)
	v_lshlrev_b32_e32 v8, 16, v44
	v_and_b32_e32 v9, 0xffff0000, v44
	v_exp_f32_e32 v8, v8
	s_nop 0
	v_mul_f32_e32 v5, v5, v8
	v_fma_f32 v6, v6, v8, v9
	s_waitcnt vmcnt(18)
	v_lshlrev_b32_e32 v11, 16, v45
	v_and_b32_e32 v12, 0xffff0000, v45
	v_exp_f32_e32 v11, v11
	s_nop 0
	v_mul_f32_e32 v5, v5, v11
	v_fma_f32 v6, v6, v11, v12
	s_waitcnt vmcnt(17)
	v_lshlrev_b32_e32 v8, 16, v46
	v_and_b32_e32 v9, 0xffff0000, v46
	v_exp_f32_e32 v8, v8
	s_nop 0
	v_mul_f32_e32 v5, v5, v8
	v_fma_f32 v6, v6, v8, v9
	s_waitcnt vmcnt(16)
	v_lshlrev_b32_e32 v11, 16, v47
	v_and_b32_e32 v12, 0xffff0000, v47
	v_exp_f32_e32 v11, v11
	s_nop 0
	v_mul_f32_e32 v5, v5, v11
	v_fma_f32 v6, v6, v11, v12
	s_waitcnt vmcnt(15)
	v_lshlrev_b32_e32 v8, 16, v48
	v_and_b32_e32 v9, 0xffff0000, v48
	v_exp_f32_e32 v8, v8
	s_nop 0
	v_mul_f32_e32 v5, v5, v8
	v_fma_f32 v6, v6, v8, v9
	s_waitcnt vmcnt(14)
	v_lshlrev_b32_e32 v11, 16, v49
	v_and_b32_e32 v12, 0xffff0000, v49
	v_exp_f32_e32 v11, v11
	s_nop 0
	v_mul_f32_e32 v5, v5, v11
	v_fma_f32 v6, v6, v11, v12
	s_waitcnt vmcnt(13)
	v_lshlrev_b32_e32 v8, 16, v50
	v_and_b32_e32 v9, 0xffff0000, v50
	v_exp_f32_e32 v8, v8
	s_nop 0
	v_mul_f32_e32 v5, v5, v8
	v_fma_f32 v6, v6, v8, v9
	s_waitcnt vmcnt(12)
	v_lshlrev_b32_e32 v11, 16, v51
	v_and_b32_e32 v12, 0xffff0000, v51
	v_exp_f32_e32 v11, v11
	s_nop 0
	v_mul_f32_e32 v5, v5, v11
	v_fma_f32 v6, v6, v11, v12
	s_waitcnt vmcnt(11)
	v_lshlrev_b32_e32 v8, 16, v52
	v_and_b32_e32 v9, 0xffff0000, v52
	v_exp_f32_e32 v8, v8
	s_nop 0
	v_mul_f32_e32 v5, v5, v8
	v_fma_f32 v6, v6, v8, v9
	s_waitcnt vmcnt(10)
	v_lshlrev_b32_e32 v11, 16, v53
	v_and_b32_e32 v12, 0xffff0000, v53
	v_exp_f32_e32 v11, v11
	s_nop 0
	v_mul_f32_e32 v5, v5, v11
	v_fma_f32 v6, v6, v11, v12
	s_waitcnt vmcnt(9)
	v_lshlrev_b32_e32 v8, 16, v54
	v_and_b32_e32 v9, 0xffff0000, v54
	v_exp_f32_e32 v8, v8
	s_nop 0
	v_mul_f32_e32 v5, v5, v8
	v_fma_f32 v6, v6, v8, v9
	s_waitcnt vmcnt(8)
	v_lshlrev_b32_e32 v11, 16, v55
	v_and_b32_e32 v12, 0xffff0000, v55
	v_exp_f32_e32 v11, v11
	s_nop 0
	v_mul_f32_e32 v5, v5, v11
	v_fma_f32 v6, v6, v11, v12
	s_waitcnt vmcnt(7)
	v_lshlrev_b32_e32 v8, 16, v56
	v_and_b32_e32 v9, 0xffff0000, v56
	v_exp_f32_e32 v8, v8
	s_nop 0
	v_mul_f32_e32 v5, v5, v8
	v_fma_f32 v6, v6, v8, v9
	s_waitcnt vmcnt(6)
	v_lshlrev_b32_e32 v11, 16, v57
	v_and_b32_e32 v12, 0xffff0000, v57
	v_exp_f32_e32 v11, v11
	s_nop 0
	v_mul_f32_e32 v5, v5, v11
	v_fma_f32 v6, v6, v11, v12
	s_waitcnt vmcnt(5)
	v_lshlrev_b32_e32 v8, 16, v58
	v_and_b32_e32 v9, 0xffff0000, v58
	v_exp_f32_e32 v8, v8
	s_nop 0
	v_mul_f32_e32 v5, v5, v8
	v_fma_f32 v6, v6, v8, v9
	s_waitcnt vmcnt(4)
	v_lshlrev_b32_e32 v11, 16, v59
	v_and_b32_e32 v12, 0xffff0000, v59
	v_exp_f32_e32 v11, v11
	s_nop 0
	v_mul_f32_e32 v5, v5, v11
	v_fma_f32 v6, v6, v11, v12
	s_waitcnt vmcnt(3)
	v_lshlrev_b32_e32 v8, 16, v60
	v_and_b32_e32 v9, 0xffff0000, v60
	v_exp_f32_e32 v8, v8
	s_nop 0
	v_mul_f32_e32 v5, v5, v8
	v_fma_f32 v6, v6, v8, v9
	s_waitcnt vmcnt(2)
	v_lshlrev_b32_e32 v11, 16, v61
	v_and_b32_e32 v12, 0xffff0000, v61
	v_exp_f32_e32 v11, v11
	s_nop 0
	v_mul_f32_e32 v5, v5, v11
	v_fma_f32 v6, v6, v11, v12
	s_waitcnt vmcnt(1)
	v_lshlrev_b32_e32 v8, 16, v62
	v_and_b32_e32 v9, 0xffff0000, v62
	v_exp_f32_e32 v8, v8
	s_nop 0
	v_mul_f32_e32 v5, v5, v8
	v_fma_f32 v6, v6, v8, v9
	s_waitcnt vmcnt(0)
	v_lshlrev_b32_e32 v11, 16, v63
	v_and_b32_e32 v12, 0xffff0000, v63
	v_exp_f32_e32 v11, v11
	s_nop 0
	v_mul_f32_e32 v5, v5, v11
	v_fma_f32 v6, v6, v11, v12
	global_store_dword v7, v5, s[78:79]
	global_store_dword v10, v6, s[78:79]
.Lp2b_agg_skip:
	s_or_b64 exec, exec, s[22:23]
	s_mov_b64 vcc, s[4:5]
	s_cbranch_vccnz .LBB0_543
	s_andn2_b64 vcc, exec, s[10:11]
	s_cbranch_vccnz .LBB0_542
	s_barrier
	s_branch .LBB0_542

; __device__ __forceinline__ float bf_lo(unsigned w) { return __uint_as_float(w << 16); }
; __device__ __forceinline__ float bf_hi(unsigned w) { return __uint_as_float(w & 0xffff0000u); }
; __global__ void __launch_bounds__(NTHR, 2) hybrid_block_fwd(Args a) {
;     ...
;         const int c2 = gtid & 1023, chunk = (gtid >> 10) & (NCH - 1), b = gtid >> 16;
;         f32x2 H = (f32x2){0.f, 0.f};
; #pragma unroll 4
;         for (int j = 0; j < chunk; ++j) { const f32x2 P = ((const f32x2*)(AGGP + (size_t)(b * NCH + j) * LW))[c2], Hj = ((const f32x2*)(AGGH + (size_t)(b * NCH + j) * LW))[c2]; H = P * H + Hj; }
;         const size_t r0 = (size_t)b * SEQ + (size_t)chunk * CH_L;
;         const u32x2* pab = (const u32x2*)((const unsigned*)AF + r0 * LW) + c2;
;         const unsigned* pg = (const unsigned*)(GELU_U + r0 * LW) + c2; unsigned* po = (unsigned*)(YCAT + r0 * KC + PW) + c2;
; #pragma unroll 16
;         for (int i = 0; i < CH_L; ++i) {
;             const u32x2 q = pab[(size_t)i * (LW / 2)]; const f32x2 av = (f32x2){__builtin_amdgcn_exp2f(bf_lo(q.x)), __builtin_amdgcn_exp2f(bf_lo(q.y))}, bv = (f32x2){bf_hi(q.x), bf_hi(q.y)}; const unsigned gq = pg[(size_t)i * (LW / 2)];
.LBB0_613:
	s_or_b64 exec, exec, s[0:1]
	s_waitcnt lgkmcnt(0)
	v_mov_b32_e32 v0, v212
	v_readlane_b32 s0, v248, 8
	s_barrier
	v_readlane_b32 s8, v248, 8
	s_nop 3
	s_nop 1
	v_add_u32_e32 v1, s8, v0
	v_and_b32_e32 v1, 0x3ff, v1
	v_lshlrev_b32_e32 v2, 3, v1
	v_lshlrev_b32_e32 v3, 2, v1
	v_add_u32_e32 v6, 0x100000, v2
	s_lshr_b32 s9, s8, 10
	s_and_b32 s10, s9, 63
	s_lshr_b32 s11, s9, 6
	s_lshl_b32 s21, s9, 20
	s_add_u32 s12, s92, s21
	s_addc_u32 s13, s93, 0
	s_lshl_b32 s21, s9, 19
	s_add_u32 s14, s94, s21
	s_addc_u32 s15, s95, 0
	s_add_u32 s14, s14, 0x9f00000
	s_addc_u32 s15, s15, 0
	s_mul_i32 s21, s9, 0xc0000
	s_add_u32 s18, s94, s21
	s_addc_u32 s19, s95, 0
	s_add_u32 s18, s18, 0x15f00800
	s_addc_u32 s19, s19, 0
	s_lshl_b32 s21, s11, 19
	s_add_u32 s0, s94, s21
	s_addc_u32 s1, s95, 0
	s_add_u32 s0, s0, 0x100000
	s_addc_u32 s1, s1, 0
	global_load_dwordx2 v[32:33], v2, s[12:13] nt
	global_load_dword v64, v3, s[14:15] nt
	s_add_u32 s12, s12, 0x2000
	s_addc_u32 s13, s13, 0
	s_add_u32 s14, s14, 0x1000
	s_addc_u32 s15, s15, 0
	global_load_dwordx2 v[34:35], v2, s[12:13] nt
	global_load_dword v65, v3, s[14:15] nt
	s_add_u32 s12, s12, 0x2000
	s_addc_u32 s13, s13, 0
	s_add_u32 s14, s14, 0x1000
	s_addc_u32 s15, s15, 0
	global_load_dwordx2 v[36:37], v2, s[12:13] nt
	global_load_dword v66, v3, s[14:15] nt
	s_add_u32 s12, s12, 0x2000
	s_addc_u32 s13, s13, 0
	s_add_u32 s14, s14, 0x1000
	s_addc_u32 s15, s15, 0
	global_load_dwordx2 v[38:39], v2, s[12:13] nt
	global_load_dword v67, v3, s[14:15] nt
	s_add_u32 s12, s12, 0x2000
	s_addc_u32 s13, s13, 0
	s_add_u32 s14, s14, 0x1000
	s_addc_u32 s15, s15, 0
	global_load_dwordx2 v[40:41], v2, s[12:13] nt
	global_load_dword v68, v3, s[14:15] nt
	s_add_u32 s12, s12, 0x2000
	s_addc_u32 s13, s13, 0
	s_add_u32 s14, s14, 0x1000
	s_addc_u32 s15, s15, 0
	global_load_dwordx2 v[42:43], v2, s[12:13] nt
	global_load_dword v69, v3, s[14:15] nt
	s_add_u32 s12, s12, 0x2000
	s_addc_u32 s13, s13, 0
	s_add_u32 s14, s14, 0x1000
	s_addc_u32 s15, s15, 0
	global_load_dwordx2 v[44:45], v2, s[12:13] nt
	global_load_dword v70, v3, s[14:15] nt
	s_add_u32 s12, s12, 0x2000
	s_addc_u32 s13, s13, 0
	s_add_u32 s14, s14, 0x1000
	s_addc_u32 s15, s15, 0
	global_load_dwordx2 v[46:47], v2, s[12:13] nt
	global_load_dword v71, v3, s[14:15] nt
	s_add_u32 s12, s12, 0x2000
	s_addc_u32 s13, s13, 0
	s_add_u32 s14, s14, 0x1000
	s_addc_u32 s15, s15, 0
	global_load_dwordx2 v[48:49], v2, s[12:13] nt
	global_load_dword v72, v3, s[14:15] nt
	s_add_u32 s12, s12, 0x2000
	s_addc_u32 s13, s13, 0
	s_add_u32 s14, s14, 0x1000
	s_addc_u32 s15, s15, 0
	global_load_dwordx2 v[50:51], v2, s[12:13] nt
	global_load_dword v73, v3, s[14:15] nt
	s_add_u32 s12, s12, 0x2000
	s_addc_u32 s13, s13, 0
	s_add_u32 s14, s14, 0x1000
	s_addc_u32 s15, s15, 0
	global_load_dwordx2 v[52:53], v2, s[12:13] nt
	global_load_dword v74, v3, s[14:15] nt
	s_add_u32 s12, s12, 0x2000
	s_addc_u32 s13, s13, 0
	s_add_u32 s14, s14, 0x1000
	s_addc_u32 s15, s15, 0
	global_load_dwordx2 v[54:55], v2, s[12:13] nt
	global_load_dword v75, v3, s[14:15] nt
	s_add_u32 s12, s12, 0x2000
	s_addc_u32 s13, s13, 0
	s_add_u32 s14, s14, 0x1000
	s_addc_u32 s15, s15, 0
	global_load_dwordx2 v[56:57], v2, s[12:13] nt
	global_load_dword v76, v3, s[14:15] nt
	s_add_u32 s12, s12, 0x2000
	s_addc_u32 s13, s13, 0
	s_add_u32 s14, s14, 0x1000
	s_addc_u32 s15, s15, 0
	global_load_dwordx2 v[58:59], v2, s[12:13] nt
	global_load_dword v77, v3, s[14:15] nt
	s_add_u32 s12, s12, 0x2000
	s_addc_u32 s13, s13, 0
	s_add_u32 s14, s14, 0x1000
	s_addc_u32 s15, s15, 0
	global_load_dwordx2 v[60:61], v2, s[12:13] nt
	global_load_dword v78, v3, s[14:15] nt
	s_add_u32 s12, s12, 0x2000
	s_addc_u32 s13, s13, 0
	s_add_u32 s14, s14, 0x1000
	s_addc_u32 s15, s15, 0
	global_load_dwordx2 v[62:63], v2, s[12:13] nt
	global_load_dword v79, v3, s[14:15] nt
	s_add_u32 s12, s12, 0x2000
	s_addc_u32 s13, s13, 0
	s_add_u32 s14, s14, 0x1000
	s_addc_u32 s15, s15, 0
	v_mov_b32_e32 v4, 0
	v_mov_b32_e32 v5, 0
	s_cmp_eq_u32 s10, 0
	s_cbranch_scc1 .Lp2d_prefix_done
